# pvprio + s_setprio 1 also over the leading QK MFMAs (first LDS wait .. first row-max VALU) of every attention body
# baseline (speedup 1.0000x reference)
; template <int MODE> ...
;     ...
;         if (t >= act0 && t < act0 + actn) {
;         const LAS unsigned char* Sl = ring + ((t + base) % 3) * SLOT;
; #pragma unroll
;         for (int hf = 0; hf < NH; ++hf) {
;             if (MODE == 1) { const int ks = ktok0 + 64 * t + 32 * hf;
;                 if (ks + 31 < qtok0 - 128 || ks > qtok0 + 31 + 128) continue; }
;             bf16x8 kf[2][2][2];
; #pragma unroll
;             for (int jj = 0; jj < 2; ++jj)
; #pragma unroll
;                 for (int kt = 0; kt < 2; ++kt)
; #pragma unroll
;                     for (int ks = 0; ks < 2; ++ks) kf[jj][kt][ks] = *(const LAS bf16x8*)(Sl + kad[jj][ks] + (32 * hf + 16 * kt) * 128);
;             f32x4 bb[2][2];
; #pragma unroll
;             for (int jj = 0; jj < 2; ++jj) { const LAS f32x4* bl = bcp + ((MODE == 0) ? (dr0 + t - act0) * 8 : 16 * t + 8 * hf) + bofs[jj];
; #pragma unroll
;                 for (int kt = 0; kt < 2; ++kt) bb[jj][kt] = bl[4 * kt]; }
;             s16x4 vlo[2][4], vhi[2][4];
; #pragma unroll
;             for (int jj = 0; jj < 2; ++jj)
; #pragma unroll
;                 for (int dt = 0; dt < 4; ++dt) { const LAS unsigned char* vp = Sl + vad[jj] + (32 * hf) * 128 + ((dt ^ sv) << 5);
;                     vlo[jj][dt] = __builtin_bit_cast(s16x4, __builtin_amdgcn_ds_read_tr16_b64_v4i16((LAS s16x4*)(vp)));
;                     vhi[jj][dt] = __builtin_bit_cast(s16x4, __builtin_amdgcn_ds_read_tr16_b64_v4i16((LAS s16x4*)(vp + 2048))); }
;             __builtin_amdgcn_sched_barrier(0);
;             f32x4 s[2][2];
; #pragma unroll
;             for (int jj = 0; jj < 2; ++jj)
; #pragma unroll
;                 for (int kt = 0; kt < 2; ++kt) { f32x4 a = (MODE == 0) ? bb[jj][kt] + mneg[jj][kt] : bb[jj][kt];
;                     a = __builtin_amdgcn_mfma_f32_16x16x32_bf16(kf[jj][kt][0], qf[jj][0], a, 0, 0, 0);
;                     s[jj][kt] = __builtin_amdgcn_mfma_f32_16x16x32_bf16(kf[jj][kt][1], qf[jj][1], a, 0, 0, 0); }
;             u32x4 pw[2];
; #pragma unroll
;             for (int jj = 0; jj < 2; ++jj) {
;                 const float tm = vmax3(vmax3(s[jj][0][0], s[jj][0][1], s[jj][0][2]), vmax3(s[jj][0][3], s[jj][1][0], s[jj][1][1]), vmax3(s[jj][1][2], s[jj][1][3], s[jj][1][3]));
;                 const float mn = quad_max3(mrun[jj], tm);
;                 const float alpha = __builtin_amdgcn_exp2f(mrun[jj] - mn);
;                 mrun[jj] = mn;
.LBB0_278:
	s_sub_i32 s52, s25, s23
	v_lshlrev_b32_e32 v94, 5, v93
	s_add_i32 s0, s23, 7
	v_xor_b32_e32 v95, 32, v94
	v_xor_b32_e32 v96, 64, v94
	s_cmp_gt_u32 s0, 7
	v_xor_b32_e32 v97, 0x60, v94
	s_cbranch_scc1 .LBB0_291
	s_lshl_b32 s0, s86, 14
	s_add_i32 s0, s0, 0
	v_add_u32_e32 v0, s0, v89
	s_lshl_b32 s14, s52, 7
	v_add_u32_e32 v2, s0, v88
	ds_read_b128 v[6:9], v0
	ds_read_b128 v[10:13], v0 offset:2048
	ds_read_b128 v[14:17], v2
	ds_read_b128 v[34:37], v2 offset:2048
	v_add_u32_e32 v0, s0, v92
	s_add_i32 s14, s24, s14
	v_add_u32_e32 v2, s0, v91
	ds_read_b128 v[38:41], v0
	ds_read_b128 v[42:45], v0 offset:2048
	ds_read_b128 v[46:49], v2
	ds_read_b128 v[50:53], v2 offset:2048
	v_lshl_add_u32 v0, v87, 4, s14
	ds_read_b128 v[54:57], v0
	ds_read_b128 v[58:61], v0 offset:64
	v_lshl_add_u32 v0, v90, 4, s14
	ds_read_b128 v[62:65], v0
	ds_read_b128 v[66:69], v0 offset:64
	v_add3_u32 v0, v86, v122, s0
	v_add_u32_e32 v2, v0, v94
	v_add_u32_e32 v3, v0, v95
	ds_read_b64_tr_b16 v[70:71], v2 offset:8192
	ds_read_b64_tr_b16 v[72:73], v2 offset:10240
	ds_read_b64_tr_b16 v[74:75], v3 offset:8192
	ds_read_b64_tr_b16 v[76:77], v3 offset:10240
	v_add_u32_e32 v2, v0, v96
	v_add_u32_e32 v0, v0, v97
	ds_read_b64_tr_b16 v[78:79], v2 offset:8192
	ds_read_b64_tr_b16 v[80:81], v2 offset:10240
	ds_read_b64_tr_b16 v[126:127], v0 offset:8192
	ds_read_b64_tr_b16 v[128:129], v0 offset:10240
	v_add3_u32 v0, v123, v122, s0
	v_add_u32_e32 v2, v0, v94
	v_add_u32_e32 v3, v0, v95
	ds_read_b64_tr_b16 v[130:131], v2 offset:8192
	ds_read_b64_tr_b16 v[132:133], v2 offset:10240
	ds_read_b64_tr_b16 v[134:135], v3 offset:8192
	ds_read_b64_tr_b16 v[136:137], v3 offset:10240
	v_add_u32_e32 v2, v0, v96
	v_add_u32_e32 v0, v0, v97
	ds_read_b64_tr_b16 v[138:139], v2 offset:8192
	ds_read_b64_tr_b16 v[140:141], v2 offset:10240
	ds_read_b64_tr_b16 v[2:3], v0 offset:8192
	ds_read_b64_tr_b16 v[4:5], v0 offset:10240
	s_setprio 1
	s_waitcnt lgkmcnt(14)
	v_pk_add_f32 v[56:57], v[112:113], v[56:57]
	v_pk_add_f32 v[54:55], v[110:111], v[54:55]
	s_mov_b32 s0, 0xf149f2ca
	s_nop 0
	v_mfma_f32_16x16x32_bf16 v[6:9], v[6:9], v[30:33], v[54:57]
	s_nop 2
	v_pk_add_f32 v[56:57], v[114:115], v[60:61]
	v_pk_add_f32 v[54:55], v[108:109], v[58:59]
	v_mfma_f32_16x16x32_bf16 v[6:9], v[14:17], v[26:29], v[6:9]
	v_pk_add_f32 v[16:17], v[106:107], v[64:65]
	v_pk_add_f32 v[14:15], v[102:103], v[62:63]
	v_mfma_f32_16x16x32_bf16 v[10:13], v[10:13], v[30:33], v[54:57]
	v_mfma_f32_16x16x32_bf16 v[10:13], v[34:37], v[26:29], v[10:13]
	s_nop 2
	s_setprio 0
	v_maximum3_f32 v0, v6, v7, v8
	v_pk_add_f32 v[56:57], v[104:105], v[68:69]
	v_pk_add_f32 v[54:55], v[100:101], v[66:67]
	v_mfma_f32_16x16x32_bf16 v[14:17], v[38:41], v[22:25], v[14:17]
	v_mfma_f32_16x16x32_bf16 v[14:17], v[46:49], v[18:21], v[14:17]
	v_maximum3_f32 v34, v9, v10, v11
	v_maximum3_f32 v35, v12, v13, v13
	v_maximum3_f32 v0, v0, v34, v35
	v_mov_b32_e32 v34, v0
	s_nop 1
	v_permlane16_swap_b32_e32 v0, v34
	v_maximum3_f32 v0, v0, v34, v34
	v_mov_b32_e32 v34, v0
	s_nop 1
	v_permlane32_swap_b32_e32 v0, v34
	v_maximum3_f32 v125, v0, s0, v34
	v_mfma_f32_16x16x32_bf16 v[34:37], v[42:45], v[22:25], v[54:57]
	v_sub_f32_e32 v6, v6, v125
	v_exp_f32_e32 v38, v6
	v_sub_f32_e32 v6, v7, v125
	v_mfma_f32_16x16x32_bf16 v[34:37], v[50:53], v[18:21], v[34:37]
	v_exp_f32_e32 v40, v6
	v_sub_f32_e32 v6, v8, v125
	v_exp_f32_e32 v42, v6
	v_sub_f32_e32 v6, v9, v125
	v_sub_f32_e32 v0, 0xf149f2ca, v125
	v_exp_f32_e32 v66, v6
	v_sub_f32_e32 v6, v10, v125
	v_exp_f32_e32 v68, v6
	v_sub_f32_e32 v6, v11, v125
	v_exp_f32_e32 v146, v0
	v_maximum3_f32 v0, v14, v15, v16
	v_maximum3_f32 v10, v17, v34, v35
	v_maximum3_f32 v11, v36, v37, v37
	v_maximum3_f32 v0, v0, v10, v11
	v_mov_b32_e32 v10, v0
	s_nop 1
	v_permlane16_swap_b32_e32 v0, v10
	v_maximum3_f32 v0, v0, v10, v10
	v_mov_b32_e32 v10, v0
	s_nop 1
	v_permlane32_swap_b32_e32 v0, v10
	v_maximum3_f32 v124, v0, s0, v10
	v_exp_f32_e32 v98, v6
	v_sub_f32_e32 v6, v12, v125
	v_sub_f32_e32 v0, 0xf149f2ca, v124
	v_exp_f32_e32 v142, v6
	v_sub_f32_e32 v6, v13, v125
	v_sub_f32_e32 v10, v14, v124
	v_exp_f32_e32 v147, v0
	v_exp_f32_e32 v144, v6
	v_exp_f32_e32 v39, v10
	v_sub_f32_e32 v10, v15, v124
	v_exp_f32_e32 v41, v10
	v_sub_f32_e32 v10, v16, v124
	v_sub_f32_e32 v0, v34, v124
	v_exp_f32_e32 v43, v10
	v_sub_f32_e32 v10, v17, v124
	v_exp_f32_e32 v69, v0
	v_sub_f32_e32 v0, v35, v124
	v_exp_f32_e32 v67, v10
	v_pk_mul_f32 v[10:11], v[146:147], 0 op_sel_hi:[1,0]
	v_exp_f32_e32 v99, v0
	v_sub_f32_e32 v0, v36, v124
	v_cvt_pk_bf16_f32 v6, v38, v40
	v_cvt_pk_bf16_f32 v7, v42, v66
	v_cvt_pk_bf16_f32 v8, v68, v98
	v_cvt_pk_bf16_f32 v9, v142, v144
	v_mov_b32_e32 v14, v10
	v_mov_b32_e32 v15, v10
	v_mov_b32_e32 v16, v10
	v_mov_b32_e32 v17, v10
	v_exp_f32_e32 v143, v0
	v_sub_f32_e32 v0, v37, v124
	v_mfma_f32_16x16x32_bf16 v[54:57], v[70:73], v[6:9], v[14:17]
	v_exp_f32_e32 v145, v0
	v_mov_b32_e32 v10, v11
	v_mov_b32_e32 v12, v11
	s_setprio 1
	s_waitcnt lgkmcnt(12)
	v_mfma_f32_16x16x32_bf16 v[62:65], v[74:77], v[6:9], v[14:17]
	v_mov_b32_e32 v13, v11
	v_cvt_pk_bf16_f32 v34, v39, v41
	v_cvt_pk_bf16_f32 v35, v43, v67
	s_waitcnt lgkmcnt(10)
	v_mfma_f32_16x16x32_bf16 v[58:61], v[78:81], v[6:9], v[14:17]
	v_cvt_pk_bf16_f32 v36, v69, v99
	v_cvt_pk_bf16_f32 v37, v143, v145
	s_waitcnt lgkmcnt(8)
	v_mfma_f32_16x16x32_bf16 v[50:53], v[126:129], v[6:9], v[14:17]
	v_add_f32_e64 v6, v38, 0
	v_add_f32_e64 v7, v39, 0
	v_pk_add_f32 v[6:7], v[40:41], v[6:7]
	s_waitcnt lgkmcnt(6)
	v_mfma_f32_16x16x32_bf16 v[46:49], v[130:133], v[34:37], v[10:13]
	v_pk_add_f32 v[6:7], v[42:43], v[6:7]
	v_pk_add_f32 v[6:7], v[66:67], v[6:7]
	s_waitcnt lgkmcnt(4)
	v_mfma_f32_16x16x32_bf16 v[42:45], v[134:137], v[34:37], v[10:13]
	v_pk_add_f32 v[6:7], v[68:69], v[6:7]
	v_pk_add_f32 v[6:7], v[98:99], v[6:7]
	s_waitcnt lgkmcnt(2)
	v_mfma_f32_16x16x32_bf16 v[38:41], v[138:141], v[34:37], v[10:13]
	v_pk_add_f32 v[6:7], v[142:143], v[6:7]
	v_pk_add_f32 v[6:7], v[144:145], v[6:7]
	s_waitcnt lgkmcnt(0)
	v_mfma_f32_16x16x32_bf16 v[34:37], v[2:5], v[34:37], v[10:13]
	s_setprio 0
	v_fma_f32 v98, v146, 0, v6
	v_fma_f32 v99, v147, 0, v7
	s_cmp_eq_u32 s41, 1
	s_cbranch_scc1 .LBB0_281
	s_branch .LBB0_292

; #define LAS __attribute__((address_space(3)))
; #define GAS __attribute__((address_space(1)))
; template <int MODE> ...
;     ...
;         if (t >= act0 && t < act0 + actn) {
;         const LAS unsigned char* Sl = ring + ((t + base) % 3) * SLOT;
; #pragma unroll
;         for (int hf = 0; hf < NH; ++hf) {
;             if (MODE == 1) { const int ks = ktok0 + 64 * t + 32 * hf;
;                 if (ks + 31 < qtok0 - 128 || ks > qtok0 + 31 + 128) continue; }
;             bf16x8 kf[2][2][2];
; #pragma unroll
;             for (int jj = 0; jj < 2; ++jj)
; #pragma unroll
;                 for (int kt = 0; kt < 2; ++kt)
; #pragma unroll
;                     for (int ks = 0; ks < 2; ++ks) kf[jj][kt][ks] = *(const LAS bf16x8*)(Sl + kad[jj][ks] + (32 * hf + 16 * kt) * 128);
;             f32x4 bb[2][2];
; #pragma unroll
;             for (int jj = 0; jj < 2; ++jj) { const LAS f32x4* bl = bcp + ((MODE == 0) ? (dr0 + t - act0) * 8 : 16 * t + 8 * hf) + bofs[jj];
; #pragma unroll
;                 for (int kt = 0; kt < 2; ++kt) bb[jj][kt] = bl[4 * kt]; }
;             s16x4 vlo[2][4], vhi[2][4];
; #pragma unroll
;             for (int jj = 0; jj < 2; ++jj)
; #pragma unroll
;                 for (int dt = 0; dt < 4; ++dt) { const LAS unsigned char* vp = Sl + vad[jj] + (32 * hf) * 128 + ((dt ^ sv) << 5);
;                     vlo[jj][dt] = __builtin_bit_cast(s16x4, __builtin_amdgcn_ds_read_tr16_b64_v4i16((LAS s16x4*)(vp)));
;                     vhi[jj][dt] = __builtin_bit_cast(s16x4, __builtin_amdgcn_ds_read_tr16_b64_v4i16((LAS s16x4*)(vp + 2048))); }
;             __builtin_amdgcn_sched_barrier(0);
;     ...
;     for (int t = 0; t < nT - 1; ++t) { head(t); body(t); }
;     head(nT - 1);
;     bf16x8 qn[2][2];
;     { const GAS bf16_t* qs = nQ ? (const GAS bf16_t*)nQ : (const GAS bf16_t*)proj + (size_t)qtok0 * NIN + qcol;
; #pragma unroll
;       for (int jj = 0; jj < 2; ++jj)
; #pragma unroll
;           for (int ks = 0; ks < 2; ++ks) qn[jj][ks] = *(const GAS bf16x8*)(qs + (size_t)(16 * jj) * NIN + 32 * ks + qoff); }
;     body(nT - 1);
.LBB0_283:
	s_add_i32 s42, s86, s26
	s_add_i32 s0, s42, 1
	s_mul_hi_i32 s14, s0, 0x55555556
	s_lshr_b32 s15, s14, 31
	s_add_i32 s14, s14, s15
	s_mul_i32 s14, s14, 3
	s_sub_i32 s0, s0, s14
	s_lshl_b32 s0, s0, 14
	s_add_i32 s0, s0, s94
	s_add_u32 s34, s34, 0x48000
	s_addc_u32 s35, s35, 0
	s_add_u32 s30, s30, 0x48000
	s_barrier
	s_addc_u32 s31, s31, 0
	s_mov_b32 m0, s0
	s_nop 0
	global_load_lds_dwordx4 v84, s[34:35]
	s_add_u32 m0, m0, 0x2000
	s_nop 0
	global_load_lds_dwordx4 v85, s[30:31]
	v_lshl_add_u64 v[6:7], v[82:83], 1, s[38:39]
	global_load_dwordx4 v[2:5], v[6:7], off
	global_load_dwordx4 v[10:13], v[6:7], off offset:64
	v_add_co_u32_e32 v6, vcc, 0x12000, v6
	s_cmp_gt_u32 s40, s27
	s_nop 0
	v_addc_co_u32_e32 v7, vcc, 0, v7, vcc
	global_load_dwordx4 v[14:17], v[6:7], off
	s_nop 0
	global_load_dwordx4 v[6:9], v[6:7], off offset:64
	s_cselect_b64 s[30:31], -1, 0
	s_add_i32 s0, s23, 8
	s_cmp_le_i32 s26, s0
	s_cselect_b64 s[26:27], -1, 0
	s_and_b64 s[26:27], s[30:31], s[26:27]
	s_and_b64 vcc, exec, s[26:27]
	s_cbranch_vccz .LBB0_285
	s_add_i32 s0, s41, s86
	s_mul_hi_i32 s14, s0, 0x55555556
	s_lshr_b32 s15, s14, 31
	s_add_i32 s14, s14, s15
	s_mul_i32 s14, s14, 3
	s_sub_i32 s0, s0, s14
	s_lshl_b32 s0, s0, 14
	s_sub_i32 s14, s41, s23
	s_add_i32 s0, s0, 0
	s_add_i32 s14, s14, s25
	v_add_u32_e32 v0, s0, v89
	s_lshl_b32 s14, s14, 7
	v_add_u32_e32 v66, s0, v88
	ds_read_b128 v[126:129], v0
	ds_read_b128 v[130:133], v0 offset:2048
	ds_read_b128 v[134:137], v66
	ds_read_b128 v[138:141], v66 offset:2048
	v_add_u32_e32 v0, s0, v92
	s_add_i32 s24, s24, s14
	v_add_u32_e32 v66, s0, v91
	ds_read_b128 v[142:145], v0
	ds_read_b128 v[146:149], v0 offset:2048
	ds_read_b128 v[150:153], v66
	ds_read_b128 v[154:157], v66 offset:2048
	v_lshl_add_u32 v0, v87, 4, s24
	ds_read_b128 v[158:161], v0
	ds_read_b128 v[162:165], v0 offset:64
	v_lshl_add_u32 v0, v90, 4, s24
	ds_read_b128 v[166:169], v0
	ds_read_b128 v[170:173], v0 offset:64
	v_lshlrev_b32_e32 v0, 5, v93
	v_add3_u32 v66, v86, v122, s0
	v_add_u32_e32 v67, v66, v0
	v_xor_b32_e32 v68, 32, v0
	v_add_u32_e32 v69, v66, v68
	ds_read_b64_tr_b16 v[94:95], v67 offset:8192
	ds_read_b64_tr_b16 v[96:97], v67 offset:10240
	ds_read_b64_tr_b16 v[90:91], v69 offset:8192
	ds_read_b64_tr_b16 v[92:93], v69 offset:10240
	v_xor_b32_e32 v67, 64, v0
	v_xor_b32_e32 v70, 0x60, v0
	v_add_u32_e32 v69, v66, v67
	v_add_u32_e32 v66, v66, v70
	ds_read_b64_tr_b16 v[86:87], v69 offset:8192
	ds_read_b64_tr_b16 v[88:89], v69 offset:10240
	ds_read_b64_tr_b16 v[82:83], v66 offset:8192
	ds_read_b64_tr_b16 v[84:85], v66 offset:10240
	v_add3_u32 v66, v123, v122, s0
	v_add_u32_e32 v0, v66, v0
	v_add_u32_e32 v68, v66, v68
	ds_read_b64_tr_b16 v[78:79], v0 offset:8192
	ds_read_b64_tr_b16 v[80:81], v0 offset:10240
	ds_read_b64_tr_b16 v[74:75], v68 offset:8192
	ds_read_b64_tr_b16 v[76:77], v68 offset:10240
	v_add_u32_e32 v0, v66, v67
	v_add_u32_e32 v68, v66, v70
	ds_read_b64_tr_b16 v[70:71], v0 offset:8192
	ds_read_b64_tr_b16 v[72:73], v0 offset:10240
	ds_read_b64_tr_b16 v[66:67], v68 offset:8192
	ds_read_b64_tr_b16 v[68:69], v68 offset:10240
	s_setprio 1
	s_waitcnt lgkmcnt(14)
; __device__ __forceinline__ unsigned cvtpk(float lo, float hi) { f32x2 v = {lo, hi}; bf16x2_t b = __builtin_convertvector(v, bf16x2_t); return __builtin_bit_cast(unsigned, b); }
; __device__ __forceinline__ float vmax3(float a, float b, float c) { return __builtin_elementwise_maximum(__builtin_elementwise_maximum(a, b), c); }
; template <int MODE> ...
;     ...
;             f32x4 s[2][2];
; #pragma unroll
;             for (int jj = 0; jj < 2; ++jj)
; #pragma unroll
;                 for (int kt = 0; kt < 2; ++kt) { f32x4 a = (MODE == 0) ? bb[jj][kt] + mneg[jj][kt] : bb[jj][kt];
;                     a = __builtin_amdgcn_mfma_f32_16x16x32_bf16(kf[jj][kt][0], qf[jj][0], a, 0, 0, 0);
;                     s[jj][kt] = __builtin_amdgcn_mfma_f32_16x16x32_bf16(kf[jj][kt][1], qf[jj][1], a, 0, 0, 0); }
;             u32x4 pw[2];
; #pragma unroll
;             for (int jj = 0; jj < 2; ++jj) {
;                 const float tm = vmax3(vmax3(s[jj][0][0], s[jj][0][1], s[jj][0][2]), vmax3(s[jj][0][3], s[jj][1][0], s[jj][1][1]), vmax3(s[jj][1][2], s[jj][1][3], s[jj][1][3]));
;                 const float mn = quad_max3(mrun[jj], tm);
;                 const float alpha = __builtin_amdgcn_exp2f(mrun[jj] - mn);
;                 mrun[jj] = mn;
;                 float rsum = 0.f;
; #pragma unroll
;                 for (int kt = 0; kt < 2; ++kt)
; #pragma unroll
;                     for (int e = 0; e < 4; ++e) { s[jj][kt][e] = __builtin_amdgcn_exp2f(s[jj][kt][e] - mn); rsum += s[jj][kt][e]; }
;                 lrun[jj] = lrun[jj] * alpha + rsum;
; #pragma unroll
;                 for (int dt = 0; dt < 4; ++dt) o[jj][dt] *= alpha;
;                 pw[jj].x = cvtpk(s[jj][0][0], s[jj][0][1]); pw[jj].y = cvtpk(s[jj][0][2], s[jj][0][3]); pw[jj].z = cvtpk(s[jj][1][0], s[jj][1][1]); pw[jj].w = cvtpk(s[jj][1][2], s[jj][1][3]);
;             }
; #pragma unroll
;             for (int jj = 0; jj < 2; ++jj)
; #pragma unroll
;                 for (int dt = 0; dt < 4; ++dt) {
;                     const bf16x8 vf = (bf16x8){vlo[jj][dt][0], vlo[jj][dt][1], vlo[jj][dt][2], vlo[jj][dt][3], vhi[jj][dt][0], vhi[jj][dt][1], vhi[jj][dt][2], vhi[jj][dt][3]};
;                     o[jj][dt] = __builtin_amdgcn_mfma_f32_16x16x32_bf16(vf, __builtin_bit_cast(bf16x8, pw[jj]), o[jj][dt], 0, 0, 0); }
;             __builtin_amdgcn_sched_barrier(0);
	v_pk_add_f32 v[112:113], v[112:113], v[160:161]
	v_pk_add_f32 v[110:111], v[110:111], v[158:159]
	v_pk_add_f32 v[114:115], v[114:115], v[164:165]
	v_pk_add_f32 v[100:101], v[100:101], v[170:171]
	v_mfma_f32_16x16x32_bf16 v[110:113], v[126:129], v[30:33], v[110:113]
	v_mfma_f32_16x16x32_bf16 v[126:129], v[134:137], v[26:29], v[110:113]
	s_nop 6
	v_pk_add_f32 v[112:113], v[108:109], v[162:163]
	s_setprio 0
	v_maximum3_f32 v0, v126, v127, v128
	v_pk_add_f32 v[108:109], v[106:107], v[168:169]
	v_mfma_f32_16x16x32_bf16 v[30:33], v[130:133], v[30:33], v[112:115]
	v_pk_add_f32 v[106:107], v[102:103], v[166:167]
	v_pk_add_f32 v[102:103], v[104:105], v[172:173]
	v_mfma_f32_16x16x32_bf16 v[26:29], v[138:141], v[26:29], v[30:33]
	s_nop 7
	v_maximum3_f32 v30, v129, v26, v27
	v_maximum3_f32 v31, v28, v29, v29
	v_maximum3_f32 v0, v0, v30, v31
	v_mov_b32_e32 v104, v0
	s_nop 1
	v_permlane16_swap_b32_e32 v0, v104
	v_mfma_f32_16x16x32_bf16 v[30:33], v[142:145], v[22:25], v[106:109]
	v_maximum3_f32 v0, v0, v104, v104
	v_mov_b32_e32 v104, v0
	s_nop 1
	v_permlane32_swap_b32_e32 v0, v104
	v_mfma_f32_16x16x32_bf16 v[22:25], v[146:149], v[22:25], v[100:103]
	v_maximum3_f32 v0, v125, v0, v104
	v_mfma_f32_16x16x32_bf16 v[30:33], v[150:153], v[18:21], v[30:33]
	s_nop 0
	v_sub_f32_e32 v100, v125, v0
	v_exp_f32_e32 v122, v100
	v_sub_f32_e32 v101, v126, v0
	v_mfma_f32_16x16x32_bf16 v[18:21], v[154:157], v[18:21], v[22:25]
	v_exp_f32_e32 v104, v101
	v_pk_mul_f32 v[60:61], v[60:61], v[122:123] op_sel_hi:[1,0]
	v_pk_mul_f32 v[58:59], v[58:59], v[122:123] op_sel_hi:[1,0]
	v_sub_f32_e32 v22, v127, v0
	v_exp_f32_e32 v106, v22
	v_sub_f32_e32 v22, v128, v0
	v_exp_f32_e32 v108, v22
	v_sub_f32_e32 v22, v129, v0
	v_exp_f32_e32 v110, v22
	v_sub_f32_e32 v22, v26, v0
	v_exp_f32_e32 v112, v22
	v_sub_f32_e32 v22, v27, v0
	v_exp_f32_e32 v114, v22
	v_sub_f32_e32 v22, v28, v0
	v_sub_f32_e32 v0, v29, v0
	v_exp_f32_e32 v126, v22
	v_exp_f32_e32 v128, v0
	v_pk_mul_f32 v[22:23], v[54:55], v[122:123] op_sel_hi:[1,0]
	v_maximum3_f32 v0, v30, v31, v32
	v_maximum3_f32 v54, v33, v18, v19
	v_maximum3_f32 v55, v20, v21, v21
	v_maximum3_f32 v0, v0, v54, v55
	v_mov_b32_e32 v54, v0
	s_nop 1
	v_permlane16_swap_b32_e32 v0, v54
	v_maximum3_f32 v0, v0, v54, v54
	v_mov_b32_e32 v54, v0
	s_nop 1
	v_permlane32_swap_b32_e32 v0, v54
	v_maximum3_f32 v0, v124, v0, v54
	v_sub_f32_e32 v30, v30, v0
	v_exp_f32_e32 v105, v30
	v_sub_f32_e32 v30, v31, v0
	v_exp_f32_e32 v107, v30
	v_sub_f32_e32 v30, v32, v0
	v_sub_f32_e32 v18, v18, v0
	v_exp_f32_e32 v109, v30
	v_sub_f32_e32 v30, v33, v0
	v_exp_f32_e32 v113, v18
	v_sub_f32_e32 v18, v19, v0
	v_sub_f32_e32 v54, v124, v0
	v_exp_f32_e32 v111, v30
	v_exp_f32_e32 v115, v18
	v_sub_f32_e32 v18, v20, v0
	v_pk_mul_f32 v[24:25], v[56:57], v[122:123] op_sel_hi:[1,0]
	v_pk_mul_f32 v[28:29], v[64:65], v[122:123] op_sel_hi:[1,0]
	v_pk_mul_f32 v[26:27], v[62:63], v[122:123] op_sel_hi:[1,0]
	v_pk_mul_f32 v[52:53], v[52:53], v[122:123] op_sel_hi:[1,0]
	v_pk_mul_f32 v[50:51], v[50:51], v[122:123] op_sel_hi:[1,0]
	v_exp_f32_e32 v127, v18
	v_sub_f32_e32 v0, v21, v0
	v_exp_f32_e32 v123, v54
	v_pk_add_f32 v[18:19], v[104:105], 0 op_sel_hi:[1,0]
	v_exp_f32_e32 v129, v0
	v_pk_add_f32 v[18:19], v[106:107], v[18:19]
	v_cvt_pk_bf16_f32 v100, v104, v106
	v_pk_add_f32 v[18:19], v[108:109], v[18:19]
	v_cvt_pk_bf16_f32 v101, v108, v110
	v_pk_add_f32 v[18:19], v[110:111], v[18:19]
	v_cvt_pk_bf16_f32 v102, v112, v114
	v_cvt_pk_bf16_f32 v103, v126, v128
	v_pk_add_f32 v[18:19], v[112:113], v[18:19]
	v_mov_b32_e32 v0, v123
	v_mfma_f32_16x16x32_bf16 v[54:57], v[94:97], v[100:103], v[22:25]
	v_pk_mul_f32 v[20:21], v[48:49], v[0:1] op_sel_hi:[1,0]
	s_setprio 1
	s_waitcnt lgkmcnt(12)
	v_mfma_f32_16x16x32_bf16 v[62:65], v[90:93], v[100:103], v[26:29]
	v_cvt_pk_bf16_f32 v22, v105, v107
	v_cvt_pk_bf16_f32 v23, v109, v111
	v_cvt_pk_bf16_f32 v24, v113, v115
	v_pk_add_f32 v[26:27], v[114:115], v[18:19]
	v_pk_mul_f32 v[18:19], v[46:47], v[0:1] op_sel_hi:[1,0]
	v_cvt_pk_bf16_f32 v25, v127, v129
	s_waitcnt lgkmcnt(10)
	v_mfma_f32_16x16x32_bf16 v[58:61], v[86:89], v[100:103], v[58:61]
	v_pk_add_f32 v[26:27], v[126:127], v[26:27]
	v_pk_add_f32 v[26:27], v[128:129], v[26:27]
	s_waitcnt lgkmcnt(6)
	v_mfma_f32_16x16x32_bf16 v[46:49], v[78:81], v[22:25], v[18:21]
	v_fma_f32 v98, v98, v122, v26
	v_fma_f32 v99, v99, v123, v27
	s_nop 0
	v_pk_mul_f32 v[20:21], v[44:45], v[0:1] op_sel_hi:[1,0]
	v_pk_mul_f32 v[18:19], v[42:43], v[0:1] op_sel_hi:[1,0]
	v_mfma_f32_16x16x32_bf16 v[50:53], v[82:85], v[100:103], v[50:53]
	s_waitcnt lgkmcnt(4)
	v_mfma_f32_16x16x32_bf16 v[42:45], v[74:77], v[22:25], v[18:21]
	s_nop 2
	v_pk_mul_f32 v[20:21], v[40:41], v[0:1] op_sel_hi:[1,0]
	v_pk_mul_f32 v[18:19], v[38:39], v[0:1] op_sel_hi:[1,0]
	s_waitcnt lgkmcnt(2)
	s_nop 0
	v_mfma_f32_16x16x32_bf16 v[38:41], v[70:73], v[22:25], v[18:21]
	s_nop 2
	v_pk_mul_f32 v[20:21], v[36:37], v[0:1] op_sel_hi:[1,0]
	v_pk_mul_f32 v[18:19], v[34:35], v[0:1] op_sel_hi:[1,0]
	s_waitcnt lgkmcnt(0)
	s_setprio 0
	s_nop 0
	v_mfma_f32_16x16x32_bf16 v[34:37], v[66:69], v[22:25], v[18:21]

; #define LAS __attribute__((address_space(3)))
; template <int MODE> ...
;     ...
;         const LAS unsigned char* Sl = ring + ((t + base) % 3) * SLOT;
; #pragma unroll
;         for (int hf = 0; hf < NH; ++hf) {
;             if (MODE == 1) { const int ks = ktok0 + 64 * t + 32 * hf;
;                 if (ks + 31 < qtok0 - 128 || ks > qtok0 + 31 + 128) continue; }
;             bf16x8 kf[2][2][2];
; #pragma unroll
;             for (int jj = 0; jj < 2; ++jj)
; #pragma unroll
;                 for (int kt = 0; kt < 2; ++kt)
; #pragma unroll
;                     for (int ks = 0; ks < 2; ++ks) kf[jj][kt][ks] = *(const LAS bf16x8*)(Sl + kad[jj][ks] + (32 * hf + 16 * kt) * 128);
;             f32x4 bb[2][2];
; #pragma unroll
;             for (int jj = 0; jj < 2; ++jj) { const LAS f32x4* bl = bcp + ((MODE == 0) ? (dr0 + t - act0) * 8 : 16 * t + 8 * hf) + bofs[jj];
; #pragma unroll
;                 for (int kt = 0; kt < 2; ++kt) bb[jj][kt] = bl[4 * kt]; }
;             s16x4 vlo[2][4], vhi[2][4];
; #pragma unroll
;             for (int jj = 0; jj < 2; ++jj)
; #pragma unroll
;                 for (int dt = 0; dt < 4; ++dt) { const LAS unsigned char* vp = Sl + vad[jj] + (32 * hf) * 128 + ((dt ^ sv) << 5);
;                     vlo[jj][dt] = __builtin_bit_cast(s16x4, __builtin_amdgcn_ds_read_tr16_b64_v4i16((LAS s16x4*)(vp)));
;                     vhi[jj][dt] = __builtin_bit_cast(s16x4, __builtin_amdgcn_ds_read_tr16_b64_v4i16((LAS s16x4*)(vp + 2048))); }
;             __builtin_amdgcn_sched_barrier(0);
.LBB0_298:
	s_add_i32 s0, s86, 1
	s_mul_hi_i32 s14, s0, 0x55555556
	s_lshr_b32 s15, s14, 31
	s_add_i32 s14, s14, s15
	s_mul_i32 s14, s14, 3
	s_sub_i32 s0, s0, s14
	s_lshl_b32 s0, s0, 14
	s_add_i32 s0, s0, 0
	v_add_u32_e32 v0, s0, v89
	s_lshl_b32 s14, s52, 7
	v_add_u32_e32 v2, s0, v88
	ds_read_b128 v[126:129], v0
	ds_read_b128 v[130:133], v0 offset:2048
	ds_read_b128 v[134:137], v2
	ds_read_b128 v[138:141], v2 offset:2048
	v_add_u32_e32 v0, s0, v92
	s_add_i32 s14, s24, s14
	v_add_u32_e32 v2, s0, v91
	ds_read_b128 v[142:145], v0
	ds_read_b128 v[146:149], v0 offset:2048
	ds_read_b128 v[150:153], v2
	ds_read_b128 v[154:157], v2 offset:2048
	v_lshl_add_u32 v0, v87, 4, s14
	ds_read_b128 v[158:161], v0 offset:128
	ds_read_b128 v[162:165], v0 offset:192
	v_lshl_add_u32 v0, v90, 4, s14
	ds_read_b128 v[166:169], v0 offset:128
	ds_read_b128 v[170:173], v0 offset:192
	v_add3_u32 v0, v86, v122, s0
	v_add_u32_e32 v2, v0, v94
	v_add_u32_e32 v3, v0, v95
	ds_read_b64_tr_b16 v[78:79], v2 offset:8192
	ds_read_b64_tr_b16 v[80:81], v2 offset:10240
	ds_read_b64_tr_b16 v[74:75], v3 offset:8192
	ds_read_b64_tr_b16 v[76:77], v3 offset:10240
	v_add_u32_e32 v2, v0, v96
	v_add_u32_e32 v0, v0, v97
	ds_read_b64_tr_b16 v[70:71], v2 offset:8192
	ds_read_b64_tr_b16 v[72:73], v2 offset:10240
	ds_read_b64_tr_b16 v[66:67], v0 offset:8192
	ds_read_b64_tr_b16 v[68:69], v0 offset:10240
	v_add3_u32 v0, v123, v122, s0
	v_add_u32_e32 v2, v0, v94
	v_add_u32_e32 v3, v0, v95
	ds_read_b64_tr_b16 v[14:15], v2 offset:8192
	ds_read_b64_tr_b16 v[16:17], v2 offset:10240
	ds_read_b64_tr_b16 v[10:11], v3 offset:8192
	ds_read_b64_tr_b16 v[12:13], v3 offset:10240
	v_add_u32_e32 v2, v0, v96
	v_add_u32_e32 v0, v0, v97
	ds_read_b64_tr_b16 v[6:7], v2 offset:8192
	ds_read_b64_tr_b16 v[8:9], v2 offset:10240
	ds_read_b64_tr_b16 v[2:3], v0 offset:8192
	ds_read_b64_tr_b16 v[4:5], v0 offset:10240
	s_setprio 1
	s_waitcnt lgkmcnt(14)
; __device__ __forceinline__ unsigned cvtpk(float lo, float hi) { f32x2 v = {lo, hi}; bf16x2_t b = __builtin_convertvector(v, bf16x2_t); return __builtin_bit_cast(unsigned, b); }
; __device__ __forceinline__ float vmax3(float a, float b, float c) { return __builtin_elementwise_maximum(__builtin_elementwise_maximum(a, b), c); }
; template <int MODE> ...
;     ...
;             f32x4 s[2][2];
; #pragma unroll
;             for (int jj = 0; jj < 2; ++jj)
; #pragma unroll
;                 for (int kt = 0; kt < 2; ++kt) { f32x4 a = (MODE == 0) ? bb[jj][kt] + mneg[jj][kt] : bb[jj][kt];
;                     a = __builtin_amdgcn_mfma_f32_16x16x32_bf16(kf[jj][kt][0], qf[jj][0], a, 0, 0, 0);
;                     s[jj][kt] = __builtin_amdgcn_mfma_f32_16x16x32_bf16(kf[jj][kt][1], qf[jj][1], a, 0, 0, 0); }
;             u32x4 pw[2];
; #pragma unroll
;             for (int jj = 0; jj < 2; ++jj) {
;                 const float tm = vmax3(vmax3(s[jj][0][0], s[jj][0][1], s[jj][0][2]), vmax3(s[jj][0][3], s[jj][1][0], s[jj][1][1]), vmax3(s[jj][1][2], s[jj][1][3], s[jj][1][3]));
;                 const float mn = quad_max3(mrun[jj], tm);
;                 const float alpha = __builtin_amdgcn_exp2f(mrun[jj] - mn);
;                 mrun[jj] = mn;
;                 float rsum = 0.f;
; #pragma unroll
;                 for (int kt = 0; kt < 2; ++kt)
; #pragma unroll
;                     for (int e = 0; e < 4; ++e) { s[jj][kt][e] = __builtin_amdgcn_exp2f(s[jj][kt][e] - mn); rsum += s[jj][kt][e]; }
;                 lrun[jj] = lrun[jj] * alpha + rsum;
; #pragma unroll
;                 for (int dt = 0; dt < 4; ++dt) o[jj][dt] *= alpha;
;                 pw[jj].x = cvtpk(s[jj][0][0], s[jj][0][1]); pw[jj].y = cvtpk(s[jj][0][2], s[jj][0][3]); pw[jj].z = cvtpk(s[jj][1][0], s[jj][1][1]); pw[jj].w = cvtpk(s[jj][1][2], s[jj][1][3]);
;             }
; #pragma unroll
;             for (int jj = 0; jj < 2; ++jj)
; #pragma unroll
;                 for (int dt = 0; dt < 4; ++dt) {
;                     const bf16x8 vf = (bf16x8){vlo[jj][dt][0], vlo[jj][dt][1], vlo[jj][dt][2], vlo[jj][dt][3], vhi[jj][dt][0], vhi[jj][dt][1], vhi[jj][dt][2], vhi[jj][dt][3]};
;                     o[jj][dt] = __builtin_amdgcn_mfma_f32_16x16x32_bf16(vf, __builtin_bit_cast(bf16x8, pw[jj]), o[jj][dt], 0, 0, 0); }
;             __builtin_amdgcn_sched_barrier(0);
	v_pk_add_f32 v[160:161], v[112:113], v[160:161]
	v_pk_add_f32 v[158:159], v[110:111], v[158:159]
	s_nop 1
	v_mfma_f32_16x16x32_bf16 v[126:129], v[126:129], v[30:33], v[158:161]
	s_nop 2
	v_pk_add_f32 v[160:161], v[114:115], v[164:165]
	v_pk_add_f32 v[158:159], v[108:109], v[162:163]
	v_mfma_f32_16x16x32_bf16 v[126:129], v[134:137], v[26:29], v[126:129]
	v_pk_add_f32 v[136:137], v[106:107], v[168:169]
	v_pk_add_f32 v[134:135], v[102:103], v[166:167]
	v_mfma_f32_16x16x32_bf16 v[130:133], v[130:133], v[30:33], v[158:161]
	v_mfma_f32_16x16x32_bf16 v[130:133], v[138:141], v[26:29], v[130:133]
	s_nop 2
	s_setprio 0
	v_maximum3_f32 v0, v126, v127, v128
	v_pk_add_f32 v[160:161], v[104:105], v[172:173]
	v_pk_add_f32 v[158:159], v[100:101], v[170:171]
	v_mfma_f32_16x16x32_bf16 v[134:137], v[142:145], v[22:25], v[134:137]
	v_mfma_f32_16x16x32_bf16 v[134:137], v[150:153], v[18:21], v[134:137]
	v_maximum3_f32 v138, v129, v130, v131
	v_maximum3_f32 v139, v132, v133, v133
	v_maximum3_f32 v0, v0, v138, v139
	v_mov_b32_e32 v138, v0
	s_nop 1
	v_permlane16_swap_b32_e32 v0, v138
	v_maximum3_f32 v0, v0, v138, v138
	v_mov_b32_e32 v138, v0
	s_nop 1
	v_permlane32_swap_b32_e32 v0, v138
	v_maximum3_f32 v162, v125, v0, v138
	v_mfma_f32_16x16x32_bf16 v[138:141], v[146:149], v[22:25], v[158:161]
	v_sub_f32_e32 v0, v125, v162
	v_sub_f32_e32 v125, v126, v162
	v_exp_f32_e32 v142, v125
	v_sub_f32_e32 v125, v127, v162
	v_exp_f32_e32 v144, v125
	v_sub_f32_e32 v125, v128, v162
	v_mfma_f32_16x16x32_bf16 v[138:141], v[154:157], v[18:21], v[138:141]
	v_exp_f32_e32 v146, v125
	v_sub_f32_e32 v125, v129, v162
	v_exp_f32_e32 v148, v125
	v_sub_f32_e32 v125, v130, v162
	v_exp_f32_e32 v130, v125
	v_sub_f32_e32 v125, v131, v162
	v_exp_f32_e32 v150, v125
	v_sub_f32_e32 v125, v132, v162
	v_exp_f32_e32 v132, v0
	v_sub_f32_e32 v0, v133, v162
	v_exp_f32_e32 v152, v125
	v_exp_f32_e32 v154, v0
	v_maximum3_f32 v0, v134, v135, v136
	v_maximum3_f32 v125, v137, v138, v139
	v_maximum3_f32 v129, v140, v141, v141
	v_maximum3_f32 v0, v0, v125, v129
	v_mov_b32_e32 v125, v0
	s_nop 1
	v_permlane16_swap_b32_e32 v0, v125
	v_maximum3_f32 v0, v0, v125, v125
	v_mov_b32_e32 v125, v0
	s_nop 1
	v_permlane32_swap_b32_e32 v0, v125
	v_maximum3_f32 v156, v124, v0, v125
	v_pk_mul_f32 v[56:57], v[56:57], v[132:133] op_sel_hi:[1,0]
	v_pk_mul_f32 v[54:55], v[54:55], v[132:133] op_sel_hi:[1,0]
	v_pk_mul_f32 v[64:65], v[64:65], v[132:133] op_sel_hi:[1,0]
	v_pk_mul_f32 v[62:63], v[62:63], v[132:133] op_sel_hi:[1,0]
	v_pk_mul_f32 v[60:61], v[60:61], v[132:133] op_sel_hi:[1,0]
	v_pk_mul_f32 v[58:59], v[58:59], v[132:133] op_sel_hi:[1,0]
	v_pk_mul_f32 v[52:53], v[52:53], v[132:133] op_sel_hi:[1,0]
	v_pk_mul_f32 v[50:51], v[50:51], v[132:133] op_sel_hi:[1,0]
	v_sub_f32_e32 v0, v134, v156
	v_sub_f32_e32 v133, v139, v156
	v_exp_f32_e32 v143, v0
	v_sub_f32_e32 v0, v135, v156
	v_sub_f32_e32 v131, v136, v156
	v_exp_f32_e32 v151, v133
	v_sub_f32_e32 v133, v140, v156
	v_exp_f32_e32 v145, v0
	v_sub_f32_e32 v0, v124, v156
	v_exp_f32_e32 v147, v131
	v_sub_f32_e32 v131, v137, v156
	v_exp_f32_e32 v153, v133
	v_sub_f32_e32 v133, v141, v156
	v_exp_f32_e32 v149, v131
	v_sub_f32_e32 v131, v138, v156
	v_exp_f32_e32 v155, v133
	v_exp_f32_e32 v133, v0
	v_exp_f32_e32 v131, v131
	v_cvt_pk_bf16_f32 v126, v142, v144
	v_cvt_pk_bf16_f32 v127, v146, v148
	v_cvt_pk_bf16_f32 v128, v130, v150
	v_cvt_pk_bf16_f32 v129, v152, v154
	v_pk_add_f32 v[124:125], v[142:143], 0 op_sel_hi:[1,0]
	v_mov_b32_e32 v0, v133
	v_pk_add_f32 v[124:125], v[144:145], v[124:125]
	s_setprio 1
	s_waitcnt lgkmcnt(10)
	v_mfma_f32_16x16x32_bf16 v[58:61], v[70:73], v[126:129], v[58:61]
	v_pk_mul_f32 v[48:49], v[48:49], v[0:1] op_sel_hi:[1,0]
	v_pk_mul_f32 v[46:47], v[46:47], v[0:1] op_sel_hi:[1,0]
	v_cvt_pk_bf16_f32 v70, v143, v145
	v_cvt_pk_bf16_f32 v71, v147, v149
	v_cvt_pk_bf16_f32 v72, v131, v151
	v_cvt_pk_bf16_f32 v73, v153, v155
	v_mfma_f32_16x16x32_bf16 v[54:57], v[78:81], v[126:129], v[54:57]
	v_pk_add_f32 v[78:79], v[146:147], v[124:125]
	v_pk_add_f32 v[78:79], v[148:149], v[78:79]
	s_waitcnt lgkmcnt(6)
	v_mfma_f32_16x16x32_bf16 v[46:49], v[14:17], v[70:73], v[46:49]
	v_pk_mul_f32 v[16:17], v[44:45], v[0:1] op_sel_hi:[1,0]
	v_pk_mul_f32 v[14:15], v[42:43], v[0:1] op_sel_hi:[1,0]
	v_mfma_f32_16x16x32_bf16 v[62:65], v[74:77], v[126:129], v[62:65]
	v_pk_add_f32 v[74:75], v[130:131], v[78:79]
	v_pk_add_f32 v[74:75], v[150:151], v[74:75]
	s_waitcnt lgkmcnt(4)
	v_mfma_f32_16x16x32_bf16 v[42:45], v[10:13], v[70:73], v[14:17]
	v_pk_mul_f32 v[12:13], v[40:41], v[0:1] op_sel_hi:[1,0]
	v_pk_mul_f32 v[10:11], v[38:39], v[0:1] op_sel_hi:[1,0]
	v_mfma_f32_16x16x32_bf16 v[50:53], v[66:69], v[126:129], v[50:53]
	v_pk_add_f32 v[66:67], v[152:153], v[74:75]
	v_pk_add_f32 v[14:15], v[154:155], v[66:67]
	s_waitcnt lgkmcnt(2)
	v_mfma_f32_16x16x32_bf16 v[38:41], v[6:9], v[70:73], v[10:13]
	v_pk_mul_f32 v[8:9], v[36:37], v[0:1] op_sel_hi:[1,0]
	v_pk_mul_f32 v[6:7], v[34:35], v[0:1] op_sel_hi:[1,0]
	v_pk_fma_f32 v[98:99], v[98:99], v[132:133], v[14:15]
	s_waitcnt lgkmcnt(0)
	v_mfma_f32_16x16x32_bf16 v[34:37], v[2:5], v[70:73], v[6:9]
	s_setprio 0
	v_mov_b32_e32 v125, v162
	v_mov_b32_e32 v124, v156
	s_cmp_eq_u32 s41, 2
	s_cbranch_scc1 .LBB0_281

; #define LAS __attribute__((address_space(3)))
; template <int MODE> ...
;     ...
;         if (t >= act0 && t < act0 + actn) {
;         const LAS unsigned char* Sl = ring + ((t + base) % 3) * SLOT;
; #pragma unroll
;         for (int hf = 0; hf < NH; ++hf) {
;             if (MODE == 1) { const int ks = ktok0 + 64 * t + 32 * hf;
;                 if (ks + 31 < qtok0 - 128 || ks > qtok0 + 31 + 128) continue; }
;             bf16x8 kf[2][2][2];
; #pragma unroll
;             for (int jj = 0; jj < 2; ++jj)
; #pragma unroll
;                 for (int kt = 0; kt < 2; ++kt)
; #pragma unroll
;                     for (int ks = 0; ks < 2; ++ks) kf[jj][kt][ks] = *(const LAS bf16x8*)(Sl + kad[jj][ks] + (32 * hf + 16 * kt) * 128);
;             f32x4 bb[2][2];
; #pragma unroll
;             for (int jj = 0; jj < 2; ++jj) { const LAS f32x4* bl = bcp + ((MODE == 0) ? (dr0 + t - act0) * 8 : 16 * t + 8 * hf) + bofs[jj];
; #pragma unroll
;                 for (int kt = 0; kt < 2; ++kt) bb[jj][kt] = bl[4 * kt]; }
;             s16x4 vlo[2][4], vhi[2][4];
; #pragma unroll
;             for (int jj = 0; jj < 2; ++jj)
; #pragma unroll
;                 for (int dt = 0; dt < 4; ++dt) { const LAS unsigned char* vp = Sl + vad[jj] + (32 * hf) * 128 + ((dt ^ sv) << 5);
;                     vlo[jj][dt] = __builtin_bit_cast(s16x4, __builtin_amdgcn_ds_read_tr16_b64_v4i16((LAS s16x4*)(vp)));
;                     vhi[jj][dt] = __builtin_bit_cast(s16x4, __builtin_amdgcn_ds_read_tr16_b64_v4i16((LAS s16x4*)(vp + 2048))); }
;             __builtin_amdgcn_sched_barrier(0);
.LBB0_305:
	s_add_i32 s0, s65, 2
	s_cmp_ge_i32 s0, s23
	s_cselect_b64 s[60:61], -1, 0
	s_cmp_lt_i32 s0, s45
	s_cselect_b64 s[66:67], -1, 0
	s_and_b64 s[60:61], s[60:61], s[66:67]
	s_andn2_b64 vcc, exec, s[60:61]
	s_cbranch_vccnz .LBB0_300
	s_add_i32 s0, s86, s65
	s_add_i32 s0, s0, 2
	s_mul_hi_i32 s14, s0, 0x55555556
	s_lshr_b32 s15, s14, 31
	s_add_i32 s14, s14, s15
	s_mul_i32 s14, s14, 3
	s_sub_i32 s0, s0, s14
	s_lshl_b32 s0, s0, 14
	s_add_i32 s0, s0, 0
	v_add_u32_e32 v2, s0, v89
	v_add_u32_e32 v3, s0, v88
	ds_read_b128 v[130:133], v2
	ds_read_b128 v[134:137], v2 offset:2048
	ds_read_b128 v[138:141], v3
	ds_read_b128 v[142:145], v3 offset:2048
	v_add_u32_e32 v2, s0, v92
	v_add_u32_e32 v3, s0, v91
	ds_read_b128 v[146:149], v2
	ds_read_b128 v[150:153], v2 offset:2048
	ds_read_b128 v[154:157], v3
	ds_read_b128 v[158:161], v3 offset:2048
	v_add_u32_e32 v2, s50, v128
	v_add_u32_e32 v3, s50, v127
	ds_read_b128 v[162:165], v2
	ds_read_b128 v[166:169], v2 offset:64
	ds_read_b128 v[170:173], v3
	ds_read_b128 v[174:177], v3 offset:64
	v_add_u32_e32 v3, s0, v178
	v_add_u32_e32 v4, s0, v179
	ds_read_b64_tr_b16 v[78:79], v3 offset:8192
	ds_read_b64_tr_b16 v[80:81], v3 offset:10240
	ds_read_b64_tr_b16 v[74:75], v4 offset:8192
	ds_read_b64_tr_b16 v[76:77], v4 offset:10240
	v_add_u32_e32 v3, s0, v180
	v_add_u32_e32 v2, s0, v181
	ds_read_b64_tr_b16 v[70:71], v3 offset:8192
	ds_read_b64_tr_b16 v[72:73], v3 offset:10240
	ds_read_b64_tr_b16 v[66:67], v2 offset:8192
	ds_read_b64_tr_b16 v[68:69], v2 offset:10240
	v_add_u32_e32 v3, s0, v182
	v_add_u32_e32 v4, s0, v183
	ds_read_b64_tr_b16 v[14:15], v3 offset:8192
	ds_read_b64_tr_b16 v[16:17], v3 offset:10240
	ds_read_b64_tr_b16 v[10:11], v4 offset:8192
	ds_read_b64_tr_b16 v[12:13], v4 offset:10240
	v_add_u32_e32 v3, s0, v184
	v_add_u32_e32 v4, s0, v185
	ds_read_b64_tr_b16 v[6:7], v3 offset:8192
	ds_read_b64_tr_b16 v[8:9], v3 offset:10240
	ds_read_b64_tr_b16 v[2:3], v4 offset:8192
	ds_read_b64_tr_b16 v[4:5], v4 offset:10240
	s_setprio 1
	s_waitcnt lgkmcnt(14)
; __device__ __forceinline__ unsigned cvtpk(float lo, float hi) { f32x2 v = {lo, hi}; bf16x2_t b = __builtin_convertvector(v, bf16x2_t); return __builtin_bit_cast(unsigned, b); }
; __device__ __forceinline__ float vmax3(float a, float b, float c) { return __builtin_elementwise_maximum(__builtin_elementwise_maximum(a, b), c); }
; template <int MODE> ...
;     ...
;             f32x4 s[2][2];
; #pragma unroll
;             for (int jj = 0; jj < 2; ++jj)
; #pragma unroll
;                 for (int kt = 0; kt < 2; ++kt) { f32x4 a = (MODE == 0) ? bb[jj][kt] + mneg[jj][kt] : bb[jj][kt];
;                     a = __builtin_amdgcn_mfma_f32_16x16x32_bf16(kf[jj][kt][0], qf[jj][0], a, 0, 0, 0);
;                     s[jj][kt] = __builtin_amdgcn_mfma_f32_16x16x32_bf16(kf[jj][kt][1], qf[jj][1], a, 0, 0, 0); }
;             u32x4 pw[2];
; #pragma unroll
;             for (int jj = 0; jj < 2; ++jj) {
;                 const float tm = vmax3(vmax3(s[jj][0][0], s[jj][0][1], s[jj][0][2]), vmax3(s[jj][0][3], s[jj][1][0], s[jj][1][1]), vmax3(s[jj][1][2], s[jj][1][3], s[jj][1][3]));
;                 const float mn = quad_max3(mrun[jj], tm);
;                 const float alpha = __builtin_amdgcn_exp2f(mrun[jj] - mn);
;                 mrun[jj] = mn;
;                 float rsum = 0.f;
; #pragma unroll
;                 for (int kt = 0; kt < 2; ++kt)
; #pragma unroll
;                     for (int e = 0; e < 4; ++e) { s[jj][kt][e] = __builtin_amdgcn_exp2f(s[jj][kt][e] - mn); rsum += s[jj][kt][e]; }
;                 lrun[jj] = lrun[jj] * alpha + rsum;
; #pragma unroll
;                 for (int dt = 0; dt < 4; ++dt) o[jj][dt] *= alpha;
;                 pw[jj].x = cvtpk(s[jj][0][0], s[jj][0][1]); pw[jj].y = cvtpk(s[jj][0][2], s[jj][0][3]); pw[jj].z = cvtpk(s[jj][1][0], s[jj][1][1]); pw[jj].w = cvtpk(s[jj][1][2], s[jj][1][3]);
;             }
; #pragma unroll
;             for (int jj = 0; jj < 2; ++jj)
; #pragma unroll
;                 for (int dt = 0; dt < 4; ++dt) {
;                     const bf16x8 vf = (bf16x8){vlo[jj][dt][0], vlo[jj][dt][1], vlo[jj][dt][2], vlo[jj][dt][3], vhi[jj][dt][0], vhi[jj][dt][1], vhi[jj][dt][2], vhi[jj][dt][3]};
;                     o[jj][dt] = __builtin_amdgcn_mfma_f32_16x16x32_bf16(vf, __builtin_bit_cast(bf16x8, pw[jj]), o[jj][dt], 0, 0, 0); }
;             __builtin_amdgcn_sched_barrier(0);
	v_pk_add_f32 v[164:165], v[112:113], v[164:165]
	v_pk_add_f32 v[162:163], v[110:111], v[162:163]
	s_nop 1
	v_mfma_f32_16x16x32_bf16 v[130:133], v[130:133], v[30:33], v[162:165]
	s_nop 2
	v_pk_add_f32 v[164:165], v[114:115], v[168:169]
	v_pk_add_f32 v[162:163], v[108:109], v[166:167]
	v_mfma_f32_16x16x32_bf16 v[130:133], v[138:141], v[26:29], v[130:133]
	v_pk_add_f32 v[140:141], v[106:107], v[172:173]
	v_pk_add_f32 v[138:139], v[102:103], v[170:171]
	v_mfma_f32_16x16x32_bf16 v[134:137], v[134:137], v[30:33], v[162:165]
	v_mfma_f32_16x16x32_bf16 v[134:137], v[142:145], v[26:29], v[134:137]
	s_nop 2
	s_setprio 0
	v_maximum3_f32 v129, v130, v131, v132
	v_pk_add_f32 v[164:165], v[104:105], v[176:177]
	v_pk_add_f32 v[162:163], v[100:101], v[174:175]
	v_mfma_f32_16x16x32_bf16 v[138:141], v[146:149], v[22:25], v[138:141]
	v_mfma_f32_16x16x32_bf16 v[138:141], v[154:157], v[18:21], v[138:141]
	v_maximum3_f32 v142, v133, v134, v135
	v_maximum3_f32 v143, v136, v137, v137
	v_maximum3_f32 v129, v129, v142, v143
	v_mov_b32_e32 v142, v129
	s_nop 1
	v_permlane16_swap_b32_e32 v129, v142
	v_maximum3_f32 v129, v129, v142, v142
	v_mov_b32_e32 v142, v129
	s_nop 1
	v_permlane32_swap_b32_e32 v129, v142
	v_maximum3_f32 v129, v125, v129, v142
	v_mfma_f32_16x16x32_bf16 v[142:145], v[150:153], v[22:25], v[162:165]
	v_pk_add_f32 v[130:131], v[130:131], v[128:129] op_sel:[0,1] op_sel_hi:[1,1] neg_lo:[0,1] neg_hi:[0,1]
	v_pk_add_f32 v[132:133], v[132:133], v[128:129] op_sel:[0,1] op_sel_hi:[1,1] neg_lo:[0,1] neg_hi:[0,1]
	v_pk_add_f32 v[134:135], v[134:135], v[128:129] op_sel:[0,1] op_sel_hi:[1,1] neg_lo:[0,1] neg_hi:[0,1]
	v_pk_add_f32 v[136:137], v[136:137], v[128:129] op_sel:[0,1] op_sel_hi:[1,1] neg_lo:[0,1] neg_hi:[0,1]
	v_sub_f32_e32 v125, v125, v129
	v_mfma_f32_16x16x32_bf16 v[142:145], v[158:161], v[18:21], v[142:145]
	v_exp_f32_e32 v146, v130
	v_exp_f32_e32 v148, v131
	v_exp_f32_e32 v150, v132
	v_exp_f32_e32 v152, v133
	v_exp_f32_e32 v154, v135
	v_exp_f32_e32 v156, v136
	v_exp_f32_e32 v158, v137
	v_exp_f32_e32 v134, v134
	v_exp_f32_e32 v136, v125
	v_maximum3_f32 v125, v138, v139, v140
	v_maximum3_f32 v133, v141, v142, v143
	v_maximum3_f32 v135, v144, v145, v145
	v_maximum3_f32 v125, v125, v133, v135
	v_mov_b32_e32 v133, v125
	s_nop 1
	v_permlane16_swap_b32_e32 v125, v133
	v_maximum3_f32 v125, v125, v133, v133
	v_mov_b32_e32 v133, v125
	s_nop 1
	v_permlane32_swap_b32_e32 v125, v133
	v_maximum3_f32 v160, v124, v125, v133
	v_pk_add_f32 v[138:139], v[138:139], v[160:161] op_sel_hi:[1,0] neg_lo:[0,1] neg_hi:[0,1]
	v_pk_add_f32 v[140:141], v[140:141], v[160:161] op_sel_hi:[1,0] neg_lo:[0,1] neg_hi:[0,1]
	v_pk_add_f32 v[142:143], v[142:143], v[160:161] op_sel_hi:[1,0] neg_lo:[0,1] neg_hi:[0,1]
	v_pk_add_f32 v[144:145], v[144:145], v[160:161] op_sel_hi:[1,0] neg_lo:[0,1] neg_hi:[0,1]
	v_sub_f32_e32 v137, v124, v160
	v_exp_f32_e32 v147, v138
	v_pk_mul_f32 v[56:57], v[56:57], v[136:137] op_sel_hi:[1,0]
	v_exp_f32_e32 v149, v139
	v_pk_mul_f32 v[54:55], v[54:55], v[136:137] op_sel_hi:[1,0]
	v_exp_f32_e32 v151, v140
	v_pk_mul_f32 v[64:65], v[64:65], v[136:137] op_sel_hi:[1,0]
	v_exp_f32_e32 v153, v141
	v_pk_mul_f32 v[62:63], v[62:63], v[136:137] op_sel_hi:[1,0]
	v_exp_f32_e32 v155, v143
	v_pk_mul_f32 v[60:61], v[60:61], v[136:137] op_sel_hi:[1,0]
	v_exp_f32_e32 v157, v144
	v_pk_mul_f32 v[58:59], v[58:59], v[136:137] op_sel_hi:[1,0]
	v_exp_f32_e32 v159, v145
	v_pk_mul_f32 v[52:53], v[52:53], v[136:137] op_sel_hi:[1,0]
	v_exp_f32_e32 v135, v142
	v_pk_mul_f32 v[50:51], v[50:51], v[136:137] op_sel_hi:[1,0]
	v_exp_f32_e32 v137, v137
	v_cvt_pk_bf16_f32 v130, v146, v148
	v_cvt_pk_bf16_f32 v131, v150, v152
	v_cvt_pk_bf16_f32 v132, v134, v154
	v_cvt_pk_bf16_f32 v133, v156, v158
	s_setprio 1
	s_waitcnt lgkmcnt(12)
	v_mfma_f32_16x16x32_bf16 v[62:65], v[74:77], v[130:133], v[62:65]
	v_pk_add_f32 v[124:125], v[146:147], v[148:149]
	v_pk_mul_f32 v[48:49], v[48:49], v[136:137] op_sel:[0,1] op_sel_hi:[1,1]
	s_waitcnt lgkmcnt(10)
	v_mfma_f32_16x16x32_bf16 v[58:61], v[70:73], v[130:133], v[58:61]
	v_pk_mul_f32 v[46:47], v[46:47], v[136:137] op_sel:[0,1] op_sel_hi:[1,1]
	v_cvt_pk_bf16_f32 v70, v147, v149
	v_cvt_pk_bf16_f32 v71, v151, v153
	v_cvt_pk_bf16_f32 v72, v135, v155
	v_cvt_pk_bf16_f32 v73, v157, v159
	v_mfma_f32_16x16x32_bf16 v[54:57], v[78:81], v[130:133], v[54:57]
	v_pk_add_f32 v[78:79], v[150:151], v[124:125]
	v_pk_add_f32 v[78:79], v[152:153], v[78:79]
	s_waitcnt lgkmcnt(6)
	v_mfma_f32_16x16x32_bf16 v[46:49], v[14:17], v[70:73], v[46:49]
	v_pk_mul_f32 v[16:17], v[44:45], v[136:137] op_sel:[0,1] op_sel_hi:[1,1]
	v_pk_mul_f32 v[14:15], v[42:43], v[136:137] op_sel:[0,1] op_sel_hi:[1,1]
	v_pk_add_f32 v[74:75], v[134:135], v[78:79]
	v_mfma_f32_16x16x32_bf16 v[50:53], v[66:69], v[130:133], v[50:53]
	v_pk_add_f32 v[74:75], v[154:155], v[74:75]
	v_pk_add_f32 v[66:67], v[156:157], v[74:75]
	s_waitcnt lgkmcnt(4)
	v_mfma_f32_16x16x32_bf16 v[42:45], v[10:13], v[70:73], v[14:17]
	v_pk_mul_f32 v[12:13], v[40:41], v[136:137] op_sel:[0,1] op_sel_hi:[1,1]
	v_pk_mul_f32 v[10:11], v[38:39], v[136:137] op_sel:[0,1] op_sel_hi:[1,1]
	v_pk_add_f32 v[14:15], v[158:159], v[66:67]
	s_waitcnt lgkmcnt(2)
	v_mfma_f32_16x16x32_bf16 v[38:41], v[6:9], v[70:73], v[10:13]
	v_pk_mul_f32 v[8:9], v[36:37], v[136:137] op_sel:[0,1] op_sel_hi:[1,1]
	v_pk_mul_f32 v[6:7], v[34:35], v[136:137] op_sel:[0,1] op_sel_hi:[1,1]
	v_pk_fma_f32 v[98:99], v[98:99], v[136:137], v[14:15]
	s_waitcnt lgkmcnt(0)
	v_mfma_f32_16x16x32_bf16 v[34:37], v[2:5], v[70:73], v[6:9]
	s_setprio 0
	v_mov_b32_e32 v125, v129
	v_mov_b32_e32 v124, v160
	s_branch .LBB0_300

; #define LAS __attribute__((address_space(3)))
; template <int MODE> ...
;     ...
;             if (MODE == 1) { const int ks = ktok0 + 64 * t + 32 * hf;
;                 if (ks + 31 < qtok0 - 128 || ks > qtok0 + 31 + 128) continue; }
;             bf16x8 kf[2][2][2];
; #pragma unroll
;             for (int jj = 0; jj < 2; ++jj)
; #pragma unroll
;                 for (int kt = 0; kt < 2; ++kt)
; #pragma unroll
;                     for (int ks = 0; ks < 2; ++ks) kf[jj][kt][ks] = *(const LAS bf16x8*)(Sl + kad[jj][ks] + (32 * hf + 16 * kt) * 128);
;             f32x4 bb[2][2];
; #pragma unroll
;             for (int jj = 0; jj < 2; ++jj) { const LAS f32x4* bl = bcp + ((MODE == 0) ? (dr0 + t - act0) * 8 : 16 * t + 8 * hf) + bofs[jj];
; #pragma unroll
;                 for (int kt = 0; kt < 2; ++kt) bb[jj][kt] = bl[4 * kt]; }
;             s16x4 vlo[2][4], vhi[2][4];
; #pragma unroll
;             for (int jj = 0; jj < 2; ++jj)
; #pragma unroll
;                 for (int dt = 0; dt < 4; ++dt) { const LAS unsigned char* vp = Sl + vad[jj] + (32 * hf) * 128 + ((dt ^ sv) << 5);
;                     vlo[jj][dt] = __builtin_bit_cast(s16x4, __builtin_amdgcn_ds_read_tr16_b64_v4i16((LAS s16x4*)(vp)));
;                     vhi[jj][dt] = __builtin_bit_cast(s16x4, __builtin_amdgcn_ds_read_tr16_b64_v4i16((LAS s16x4*)(vp + 2048))); }
;             __builtin_amdgcn_sched_barrier(0);
;             f32x4 s[2][2];
; #pragma unroll
;             for (int jj = 0; jj < 2; ++jj)
; #pragma unroll
;                 for (int kt = 0; kt < 2; ++kt) { f32x4 a = (MODE == 0) ? bb[jj][kt] + mneg[jj][kt] : bb[jj][kt];
;                     a = __builtin_amdgcn_mfma_f32_16x16x32_bf16(kf[jj][kt][0], qf[jj][0], a, 0, 0, 0);
;                     s[jj][kt] = __builtin_amdgcn_mfma_f32_16x16x32_bf16(kf[jj][kt][1], qf[jj][1], a, 0, 0, 0); }
;             u32x4 pw[2];
; #pragma unroll
;             for (int jj = 0; jj < 2; ++jj) {
;                 const float tm = vmax3(vmax3(s[jj][0][0], s[jj][0][1], s[jj][0][2]), vmax3(s[jj][0][3], s[jj][1][0], s[jj][1][1]), vmax3(s[jj][1][2], s[jj][1][3], s[jj][1][3]));
;                 const float mn = quad_max3(mrun[jj], tm);
;                 const float alpha = __builtin_amdgcn_exp2f(mrun[jj] - mn);
;                 mrun[jj] = mn;
;                 float rsum = 0.f;
; #pragma unroll
;                 for (int kt = 0; kt < 2; ++kt)
; #pragma unroll
.LBB0_343:
	s_add_i32 s0, s86, s65
	s_mul_hi_i32 s14, s0, 0x55555556
	s_lshr_b32 s15, s14, 31
	s_add_i32 s14, s14, s15
	s_mul_i32 s14, s14, 3
	s_sub_i32 s0, s0, s14
	s_lshl_b32 s0, s0, 14
	s_add_i32 s0, s0, 0
	s_add_i32 s14, s27, 31
	s_cmp_lt_i32 s14, s41
	s_cselect_b64 s[50:51], -1, 0
	s_cmp_gt_i32 s27, s45
	s_cselect_b64 s[52:53], -1, 0
	s_or_b64 s[50:51], s[50:51], s[52:53]
	v_add_u32_e32 v0, s0, v78
	s_and_b64 vcc, exec, s[50:51]
	v_add_u32_e32 v98, s0, v70
	v_add_u32_e32 v97, s0, v71
	v_add_u32_e32 v96, s40, v80
	v_add_u32_e32 v85, s40, v79
	v_add_u32_e32 v84, v0, v74
	v_add_u32_e32 v83, v0, v75
	v_add_u32_e32 v81, v0, v76
	v_add_u32_e32 v0, v0, v77
	s_cbranch_vccnz .LBB0_345
	v_add_u32_e32 v2, 0x10000, v96
	v_add_u32_e32 v3, 0x10040, v96
	ds_read_b128 v[100:103], v98
	ds_read_b128 v[104:107], v98 offset:2048
	ds_read_b128 v[108:111], v97
	ds_read_b128 v[112:115], v97 offset:2048
	ds_read_b128 v[118:121], v2
	ds_read_b128 v[122:125], v3
	v_add_u32_e32 v2, 0x10000, v85
	v_add_u32_e32 v3, 0x10040, v85
	ds_read_b128 v[126:129], v2
	ds_read_b128 v[130:133], v3
	ds_read_b64_tr_b16 v[14:15], v84 offset:8192
	ds_read_b64_tr_b16 v[16:17], v84 offset:10240
	ds_read_b64_tr_b16 v[10:11], v83 offset:8192
	ds_read_b64_tr_b16 v[12:13], v83 offset:10240
	ds_read_b64_tr_b16 v[6:7], v81 offset:8192
	ds_read_b64_tr_b16 v[8:9], v81 offset:10240
	ds_read_b64_tr_b16 v[2:3], v0 offset:8192
	ds_read_b64_tr_b16 v[4:5], v0 offset:10240
	s_setprio 1
	s_waitcnt lgkmcnt(11)
	v_mfma_f32_16x16x32_bf16 v[118:121], v[100:103], v[30:33], v[118:121]
	s_waitcnt lgkmcnt(10)
	v_mfma_f32_16x16x32_bf16 v[122:125], v[104:107], v[30:33], v[122:125]
	v_mfma_f32_16x16x32_bf16 v[118:121], v[108:111], v[26:29], v[118:121]
	v_mfma_f32_16x16x32_bf16 v[122:125], v[112:115], v[26:29], v[122:125]
	s_waitcnt lgkmcnt(9)
	v_mfma_f32_16x16x32_bf16 v[100:103], v[100:103], v[22:25], v[126:129]
	s_nop 4
	s_setprio 0
	v_maximum3_f32 v99, v118, v119, v120
	v_mfma_f32_16x16x32_bf16 v[100:103], v[108:111], v[18:21], v[100:103]
	v_maximum3_f32 v108, v121, v122, v123
	v_maximum3_f32 v109, v124, v125, v125
	v_maximum3_f32 v99, v99, v108, v109
	s_waitcnt lgkmcnt(8)
	v_mfma_f32_16x16x32_bf16 v[104:107], v[104:107], v[22:25], v[130:133]
	v_mov_b32_e32 v108, v99
	s_nop 1
	v_permlane16_swap_b32_e32 v99, v108
	v_maximum3_f32 v99, v99, v108, v108
	v_mfma_f32_16x16x32_bf16 v[104:107], v[112:115], v[18:21], v[104:107]
	v_mov_b32_e32 v108, v99
	s_nop 1
	v_permlane32_swap_b32_e32 v99, v108
	v_maximum3_f32 v99, v82, v99, v108
	v_sub_f32_e32 v82, v82, v99
	v_exp_f32_e32 v130, v82
	v_maximum3_f32 v82, v100, v101, v102
	v_maximum3_f32 v113, v103, v104, v105
	v_maximum3_f32 v115, v106, v107, v107
	v_maximum3_f32 v82, v82, v113, v115
	v_mov_b32_e32 v113, v82
	s_nop 1
	v_permlane16_swap_b32_e32 v82, v113
	v_maximum3_f32 v82, v82, v113, v113
	v_mov_b32_e32 v113, v82
	s_nop 1
	v_permlane32_swap_b32_e32 v82, v113
	v_maximum3_f32 v117, v95, v82, v113
	v_sub_f32_e32 v108, v118, v99
	v_sub_f32_e32 v82, v95, v117
	v_sub_f32_e32 v95, v100, v117
	v_exp_f32_e32 v112, v108
	v_sub_f32_e32 v108, v119, v99
	v_exp_f32_e32 v113, v95
	v_sub_f32_e32 v95, v101, v117
	v_exp_f32_e32 v114, v108
	v_sub_f32_e32 v108, v120, v99
	v_exp_f32_e32 v115, v95
	v_sub_f32_e32 v95, v102, v117
	v_exp_f32_e32 v118, v108
	v_sub_f32_e32 v108, v121, v99
	v_exp_f32_e32 v119, v95
	v_sub_f32_e32 v95, v103, v117
	v_exp_f32_e32 v120, v108
	v_sub_f32_e32 v108, v122, v99
	v_exp_f32_e32 v121, v95
	v_sub_f32_e32 v95, v104, v117
	v_exp_f32_e32 v122, v108
	v_sub_f32_e32 v108, v123, v99
	v_exp_f32_e32 v123, v95
	v_sub_f32_e32 v95, v105, v117
	v_pk_add_f32 v[100:101], v[112:113], 0 op_sel_hi:[1,0]
	v_exp_f32_e32 v126, v108
	v_sub_f32_e32 v108, v124, v99
	v_exp_f32_e32 v127, v95
	v_sub_f32_e32 v95, v106, v117
	v_pk_add_f32 v[100:101], v[114:115], v[100:101]
	v_exp_f32_e32 v124, v108
	v_sub_f32_e32 v108, v125, v99
	v_exp_f32_e32 v125, v95
	v_sub_f32_e32 v95, v107, v117
	v_pk_add_f32 v[100:101], v[118:119], v[100:101]
	v_exp_f32_e32 v128, v108
	v_pk_mul_f32 v[52:53], v[52:53], v[130:131] op_sel_hi:[1,0]
	v_pk_mul_f32 v[50:51], v[50:51], v[130:131] op_sel_hi:[1,0]
	v_pk_mul_f32 v[56:57], v[56:57], v[130:131] op_sel_hi:[1,0]
	v_pk_mul_f32 v[54:55], v[54:55], v[130:131] op_sel_hi:[1,0]
	v_pk_mul_f32 v[60:61], v[60:61], v[130:131] op_sel_hi:[1,0]
	v_pk_mul_f32 v[58:59], v[58:59], v[130:131] op_sel_hi:[1,0]
	v_pk_mul_f32 v[64:65], v[64:65], v[130:131] op_sel_hi:[1,0]
	v_pk_mul_f32 v[62:63], v[62:63], v[130:131] op_sel_hi:[1,0]
	v_exp_f32_e32 v129, v95
	v_pk_add_f32 v[100:101], v[120:121], v[100:101]
	v_exp_f32_e32 v131, v82
	v_pk_add_f32 v[100:101], v[122:123], v[100:101]
	v_cvt_pk_bf16_f32 v108, v112, v114
	v_pk_add_f32 v[100:101], v[126:127], v[100:101]
	v_mov_b32_e32 v82, v131
	v_pk_add_f32 v[100:101], v[124:125], v[100:101]
	v_cvt_pk_bf16_f32 v109, v118, v120
	v_pk_add_f32 v[100:101], v[128:129], v[100:101]
	v_cvt_pk_bf16_f32 v110, v122, v126
	v_cvt_pk_bf16_f32 v111, v124, v128
	v_pk_fma_f32 v[88:89], v[88:89], v[130:131], v[100:101]
	v_pk_mul_f32 v[36:37], v[36:37], v[82:83] op_sel_hi:[1,0]
	v_pk_mul_f32 v[34:35], v[34:35], v[82:83] op_sel_hi:[1,0]
	v_pk_mul_f32 v[40:41], v[40:41], v[82:83] op_sel_hi:[1,0]
	v_pk_mul_f32 v[38:39], v[38:39], v[82:83] op_sel_hi:[1,0]
	v_pk_mul_f32 v[44:45], v[44:45], v[82:83] op_sel_hi:[1,0]
	v_pk_mul_f32 v[42:43], v[42:43], v[82:83] op_sel_hi:[1,0]
	v_pk_mul_f32 v[48:49], v[48:49], v[82:83] op_sel_hi:[1,0]
	v_pk_mul_f32 v[46:47], v[46:47], v[82:83] op_sel_hi:[1,0]
	v_cvt_pk_bf16_f32 v100, v113, v115
	v_cvt_pk_bf16_f32 v101, v119, v121
	v_cvt_pk_bf16_f32 v102, v123, v127
	v_cvt_pk_bf16_f32 v103, v125, v129
	s_setprio 1
	s_waitcnt lgkmcnt(6)
	v_mfma_f32_16x16x32_bf16 v[50:53], v[14:17], v[108:111], v[50:53]
	s_waitcnt lgkmcnt(4)
	v_mfma_f32_16x16x32_bf16 v[54:57], v[10:13], v[108:111], v[54:57]
	s_waitcnt lgkmcnt(2)
	v_mfma_f32_16x16x32_bf16 v[58:61], v[6:9], v[108:111], v[58:61]
	s_waitcnt lgkmcnt(0)
	v_mfma_f32_16x16x32_bf16 v[62:65], v[2:5], v[108:111], v[62:65]
	v_mfma_f32_16x16x32_bf16 v[34:37], v[14:17], v[100:103], v[34:37]
	v_mfma_f32_16x16x32_bf16 v[38:41], v[10:13], v[100:103], v[38:41]
	v_mfma_f32_16x16x32_bf16 v[42:45], v[6:9], v[100:103], v[42:45]
	v_mfma_f32_16x16x32_bf16 v[46:49], v[2:5], v[100:103], v[46:49]
	s_setprio 0
	v_mov_b32_e32 v82, v99
	v_mov_b32_e32 v95, v117
; #define LAS __attribute__((address_space(3)))
; template <int MODE> ...
;     ...
;             if (MODE == 1) { const int ks = ktok0 + 64 * t + 32 * hf;
;                 if (ks + 31 < qtok0 - 128 || ks > qtok0 + 31 + 128) continue; }
;             bf16x8 kf[2][2][2];
; #pragma unroll
;             for (int jj = 0; jj < 2; ++jj)
; #pragma unroll
;                 for (int kt = 0; kt < 2; ++kt)
; #pragma unroll
;                     for (int ks = 0; ks < 2; ++ks) kf[jj][kt][ks] = *(const LAS bf16x8*)(Sl + kad[jj][ks] + (32 * hf + 16 * kt) * 128);
;             f32x4 bb[2][2];
; #pragma unroll
;             for (int jj = 0; jj < 2; ++jj) { const LAS f32x4* bl = bcp + ((MODE == 0) ? (dr0 + t - act0) * 8 : 16 * t + 8 * hf) + bofs[jj];
; #pragma unroll
;                 for (int kt = 0; kt < 2; ++kt) bb[jj][kt] = bl[4 * kt]; }
;             s16x4 vlo[2][4], vhi[2][4];
; #pragma unroll
;             for (int jj = 0; jj < 2; ++jj)
; #pragma unroll
;                 for (int dt = 0; dt < 4; ++dt) { const LAS unsigned char* vp = Sl + vad[jj] + (32 * hf) * 128 + ((dt ^ sv) << 5);
;                     vlo[jj][dt] = __builtin_bit_cast(s16x4, __builtin_amdgcn_ds_read_tr16_b64_v4i16((LAS s16x4*)(vp)));
;                     vhi[jj][dt] = __builtin_bit_cast(s16x4, __builtin_amdgcn_ds_read_tr16_b64_v4i16((LAS s16x4*)(vp + 2048))); }
;             __builtin_amdgcn_sched_barrier(0);
;             f32x4 s[2][2];
; #pragma unroll
;             for (int jj = 0; jj < 2; ++jj)
; #pragma unroll
;                 for (int kt = 0; kt < 2; ++kt) { f32x4 a = (MODE == 0) ? bb[jj][kt] + mneg[jj][kt] : bb[jj][kt];
;                     a = __builtin_amdgcn_mfma_f32_16x16x32_bf16(kf[jj][kt][0], qf[jj][0], a, 0, 0, 0);
;                     s[jj][kt] = __builtin_amdgcn_mfma_f32_16x16x32_bf16(kf[jj][kt][1], qf[jj][1], a, 0, 0, 0); }
;             u32x4 pw[2];
; #pragma unroll
;             for (int jj = 0; jj < 2; ++jj) {
;                 const float tm = vmax3(vmax3(s[jj][0][0], s[jj][0][1], s[jj][0][2]), vmax3(s[jj][0][3], s[jj][1][0], s[jj][1][1]), vmax3(s[jj][1][2], s[jj][1][3], s[jj][1][3]));
;                 const float mn = quad_max3(mrun[jj], tm);
;                 const float alpha = __builtin_amdgcn_exp2f(mrun[jj] - mn);
;                 mrun[jj] = mn;
;                 float rsum = 0.f;
; #pragma unroll
;                 for (int kt = 0; kt < 2; ++kt)
; #pragma unroll
.LBB0_345:
	s_add_i32 s0, s27, 32
	s_add_i32 s14, s27, 63
	s_cmp_lt_i32 s14, s41
	s_cselect_b64 s[50:51], -1, 0
	s_cmp_gt_i32 s0, s45
	s_cselect_b64 s[52:53], -1, 0
	s_or_b64 s[50:51], s[50:51], s[52:53]
	s_and_b64 vcc, exec, s[50:51]
	s_cbranch_vccnz .LBB0_333
	v_add_u32_e32 v2, 0x10080, v96
	v_add_u32_e32 v3, 0x100c0, v96
	ds_read_b128 v[100:103], v98 offset:4096
	ds_read_b128 v[104:107], v98 offset:6144
	ds_read_b128 v[108:111], v97 offset:4096
	ds_read_b128 v[112:115], v97 offset:6144
	ds_read_b128 v[96:99], v2
	ds_read_b128 v[118:121], v3
	v_add_u32_e32 v2, 0x10080, v85
	v_add_u32_e32 v3, 0x100c0, v85
	ds_read_b128 v[122:125], v2
	ds_read_b128 v[126:129], v3
	ds_read_b64_tr_b16 v[14:15], v84 offset:12288
	ds_read_b64_tr_b16 v[16:17], v84 offset:14336
	ds_read_b64_tr_b16 v[10:11], v83 offset:12288
	ds_read_b64_tr_b16 v[12:13], v83 offset:14336
	ds_read_b64_tr_b16 v[6:7], v81 offset:12288
	ds_read_b64_tr_b16 v[8:9], v81 offset:14336
	ds_read_b64_tr_b16 v[2:3], v0 offset:12288
	ds_read_b64_tr_b16 v[4:5], v0 offset:14336
	s_setprio 1
	s_waitcnt lgkmcnt(11)
	v_mfma_f32_16x16x32_bf16 v[96:99], v[100:103], v[30:33], v[96:99]
	s_waitcnt lgkmcnt(10)
	v_mfma_f32_16x16x32_bf16 v[118:121], v[104:107], v[30:33], v[118:121]
	v_mfma_f32_16x16x32_bf16 v[96:99], v[108:111], v[26:29], v[96:99]
	v_mfma_f32_16x16x32_bf16 v[118:121], v[112:115], v[26:29], v[118:121]
	s_waitcnt lgkmcnt(9)
	v_mfma_f32_16x16x32_bf16 v[100:103], v[100:103], v[22:25], v[122:125]
	s_nop 4
	s_setprio 0
	v_maximum3_f32 v0, v96, v97, v98
	v_maximum3_f32 v81, v99, v118, v119
	v_maximum3_f32 v83, v120, v121, v121
	v_maximum3_f32 v0, v0, v81, v83
	v_mov_b32_e32 v81, v0
	s_waitcnt lgkmcnt(8)
	v_mfma_f32_16x16x32_bf16 v[104:107], v[104:107], v[22:25], v[126:129]
	v_permlane16_swap_b32_e32 v0, v81
	v_maximum3_f32 v0, v0, v81, v81
	v_mov_b32_e32 v81, v0
	s_nop 1
	v_permlane32_swap_b32_e32 v0, v81
	v_mfma_f32_16x16x32_bf16 v[100:103], v[108:111], v[18:21], v[100:103]
	v_maximum3_f32 v81, v82, v0, v81
	v_sub_f32_e32 v0, v82, v81
	v_sub_f32_e32 v82, v96, v81
	v_mfma_f32_16x16x32_bf16 v[104:107], v[112:115], v[18:21], v[104:107]
	v_exp_f32_e32 v96, v82
	v_sub_f32_e32 v82, v97, v81
	v_exp_f32_e32 v108, v82
	v_sub_f32_e32 v82, v98, v81
	v_exp_f32_e32 v98, v82
	v_sub_f32_e32 v82, v99, v81
	v_exp_f32_e32 v122, v0
	v_maximum3_f32 v0, v100, v101, v102
	v_maximum3_f32 v97, v103, v104, v105
	v_maximum3_f32 v99, v106, v107, v107
	v_maximum3_f32 v0, v0, v97, v99
	v_mov_b32_e32 v97, v0
	s_nop 1
	v_permlane16_swap_b32_e32 v0, v97
	v_maximum3_f32 v0, v0, v97, v97
	v_mov_b32_e32 v97, v0
	s_nop 1
	v_permlane32_swap_b32_e32 v0, v97
	v_maximum3_f32 v117, v95, v0, v97
	v_sub_f32_e32 v0, v95, v117
	v_sub_f32_e32 v95, v100, v117
	v_exp_f32_e32 v97, v95
	v_sub_f32_e32 v95, v101, v117
	v_exp_f32_e32 v109, v95
	v_sub_f32_e32 v95, v102, v117
	v_exp_f32_e32 v99, v95
	v_sub_f32_e32 v95, v103, v117
	v_exp_f32_e32 v110, v82
	v_sub_f32_e32 v82, v118, v81
	v_exp_f32_e32 v111, v95
	v_sub_f32_e32 v95, v104, v117
	v_exp_f32_e32 v112, v82
	v_sub_f32_e32 v82, v119, v81
	v_exp_f32_e32 v113, v95
	v_sub_f32_e32 v95, v105, v117
	v_exp_f32_e32 v114, v82
	v_sub_f32_e32 v82, v120, v81
	v_exp_f32_e32 v115, v95
	v_sub_f32_e32 v95, v106, v117
	v_exp_f32_e32 v118, v82
	v_sub_f32_e32 v82, v121, v81
	v_pk_mul_f32 v[52:53], v[52:53], v[122:123] op_sel_hi:[1,0]
	v_pk_mul_f32 v[50:51], v[50:51], v[122:123] op_sel_hi:[1,0]
	v_pk_mul_f32 v[56:57], v[56:57], v[122:123] op_sel_hi:[1,0]
	v_pk_mul_f32 v[54:55], v[54:55], v[122:123] op_sel_hi:[1,0]
	v_pk_mul_f32 v[60:61], v[60:61], v[122:123] op_sel_hi:[1,0]
	v_pk_mul_f32 v[58:59], v[58:59], v[122:123] op_sel_hi:[1,0]
	v_pk_mul_f32 v[64:65], v[64:65], v[122:123] op_sel_hi:[1,0]
	v_pk_mul_f32 v[62:63], v[62:63], v[122:123] op_sel_hi:[1,0]
	v_exp_f32_e32 v119, v95
	v_sub_f32_e32 v95, v107, v117
	v_exp_f32_e32 v123, v0
	v_exp_f32_e32 v120, v82
	v_pk_add_f32 v[100:101], v[96:97], 0 op_sel_hi:[1,0]
	v_exp_f32_e32 v121, v95
	v_pk_add_f32 v[100:101], v[108:109], v[100:101]
	v_mov_b32_e32 v0, v123
	v_pk_add_f32 v[100:101], v[98:99], v[100:101]
	v_cvt_pk_bf16_f32 v82, v96, v108
	v_pk_add_f32 v[100:101], v[110:111], v[100:101]
	v_cvt_pk_bf16_f32 v83, v98, v110
	v_cvt_pk_bf16_f32 v84, v112, v114
	v_cvt_pk_bf16_f32 v85, v118, v120
	v_pk_add_f32 v[100:101], v[112:113], v[100:101]
	v_pk_mul_f32 v[36:37], v[36:37], v[0:1] op_sel_hi:[1,0]
	v_pk_mul_f32 v[34:35], v[34:35], v[0:1] op_sel_hi:[1,0]
	v_pk_mul_f32 v[40:41], v[40:41], v[0:1] op_sel_hi:[1,0]
	v_pk_mul_f32 v[38:39], v[38:39], v[0:1] op_sel_hi:[1,0]
	v_pk_mul_f32 v[44:45], v[44:45], v[0:1] op_sel_hi:[1,0]
	v_pk_mul_f32 v[42:43], v[42:43], v[0:1] op_sel_hi:[1,0]
	v_pk_mul_f32 v[48:49], v[48:49], v[0:1] op_sel_hi:[1,0]
	v_pk_mul_f32 v[46:47], v[46:47], v[0:1] op_sel_hi:[1,0]
	v_cvt_pk_bf16_f32 v96, v97, v109
	v_cvt_pk_bf16_f32 v97, v99, v111
	v_cvt_pk_bf16_f32 v98, v113, v115
	v_cvt_pk_bf16_f32 v99, v119, v121
	v_pk_add_f32 v[100:101], v[114:115], v[100:101]
	s_setprio 1
	s_waitcnt lgkmcnt(6)
	v_mfma_f32_16x16x32_bf16 v[50:53], v[14:17], v[82:85], v[50:53]
	v_pk_add_f32 v[100:101], v[118:119], v[100:101]
	v_pk_add_f32 v[100:101], v[120:121], v[100:101]
	s_waitcnt lgkmcnt(4)
	v_mfma_f32_16x16x32_bf16 v[54:57], v[10:13], v[82:85], v[54:57]
	v_fma_f32 v88, v88, v122, v100
	v_fma_f32 v89, v89, v123, v101
	s_waitcnt lgkmcnt(2)
	v_mfma_f32_16x16x32_bf16 v[58:61], v[6:9], v[82:85], v[58:61]
	s_waitcnt lgkmcnt(0)
	v_mfma_f32_16x16x32_bf16 v[62:65], v[2:5], v[82:85], v[62:65]
	v_mfma_f32_16x16x32_bf16 v[34:37], v[14:17], v[96:99], v[34:37]
	v_mfma_f32_16x16x32_bf16 v[38:41], v[10:13], v[96:99], v[38:41]
	v_mfma_f32_16x16x32_bf16 v[42:45], v[6:9], v[96:99], v[42:45]
	v_mfma_f32_16x16x32_bf16 v[46:49], v[2:5], v[96:99], v[46:49]
	s_setprio 0
	v_mov_b32_e32 v95, v117
	v_mov_b32_e32 v82, v81
	s_branch .LBB0_333

; #define LAS __attribute__((address_space(3)))
; template <int MODE> ...
;     ...
;             if (MODE == 1) { const int ks = ktok0 + 64 * t + 32 * hf;
;                 if (ks + 31 < qtok0 - 128 || ks > qtok0 + 31 + 128) continue; }
;             bf16x8 kf[2][2][2];
; #pragma unroll
;             for (int jj = 0; jj < 2; ++jj)
; #pragma unroll
;                 for (int kt = 0; kt < 2; ++kt)
; #pragma unroll
;                     for (int ks = 0; ks < 2; ++ks) kf[jj][kt][ks] = *(const LAS bf16x8*)(Sl + kad[jj][ks] + (32 * hf + 16 * kt) * 128);
;             f32x4 bb[2][2];
; #pragma unroll
;             for (int jj = 0; jj < 2; ++jj) { const LAS f32x4* bl = bcp + ((MODE == 0) ? (dr0 + t - act0) * 8 : 16 * t + 8 * hf) + bofs[jj];
; #pragma unroll
;                 for (int kt = 0; kt < 2; ++kt) bb[jj][kt] = bl[4 * kt]; }
;             s16x4 vlo[2][4], vhi[2][4];
; #pragma unroll
;             for (int jj = 0; jj < 2; ++jj)
; #pragma unroll
;                 for (int dt = 0; dt < 4; ++dt) { const LAS unsigned char* vp = Sl + vad[jj] + (32 * hf) * 128 + ((dt ^ sv) << 5);
;                     vlo[jj][dt] = __builtin_bit_cast(s16x4, __builtin_amdgcn_ds_read_tr16_b64_v4i16((LAS s16x4*)(vp)));
;                     vhi[jj][dt] = __builtin_bit_cast(s16x4, __builtin_amdgcn_ds_read_tr16_b64_v4i16((LAS s16x4*)(vp + 2048))); }
;             __builtin_amdgcn_sched_barrier(0);
;             f32x4 s[2][2];
; #pragma unroll
;             for (int jj = 0; jj < 2; ++jj)
; #pragma unroll
;                 for (int kt = 0; kt < 2; ++kt) { f32x4 a = (MODE == 0) ? bb[jj][kt] + mneg[jj][kt] : bb[jj][kt];
;                     a = __builtin_amdgcn_mfma_f32_16x16x32_bf16(kf[jj][kt][0], qf[jj][0], a, 0, 0, 0);
;                     s[jj][kt] = __builtin_amdgcn_mfma_f32_16x16x32_bf16(kf[jj][kt][1], qf[jj][1], a, 0, 0, 0); }
;             u32x4 pw[2];
; #pragma unroll
;             for (int jj = 0; jj < 2; ++jj) {
;                 const float tm = vmax3(vmax3(s[jj][0][0], s[jj][0][1], s[jj][0][2]), vmax3(s[jj][0][3], s[jj][1][0], s[jj][1][1]), vmax3(s[jj][1][2], s[jj][1][3], s[jj][1][3]));
;                 const float mn = quad_max3(mrun[jj], tm);
;                 const float alpha = __builtin_amdgcn_exp2f(mrun[jj] - mn);
;                 mrun[jj] = mn;
;                 float rsum = 0.f;
; #pragma unroll
;                 for (int kt = 0; kt < 2; ++kt)
; #pragma unroll
.LBB0_356:
	v_lshl_add_u64 v[6:7], v[66:67], 1, s[38:39]
	global_load_dwordx4 v[2:5], v[6:7], off
	global_load_dwordx4 v[10:13], v[6:7], off offset:64
	v_add_co_u32_e32 v6, vcc, 0x12000, v6
	s_cmp_lt_i32 s5, 1
	s_nop 0
	v_addc_co_u32_e32 v7, vcc, 0, v7, vcc
	global_load_dwordx4 v[14:17], v[6:7], off
	s_nop 0
	global_load_dwordx4 v[6:9], v[6:7], off offset:64
	s_cbranch_scc1 .LBB0_361
	s_mul_i32 s0, s22, 0x600
	s_add_i32 s27, s0, 0
	s_add_i32 s0, s26, s86
	s_mul_hi_i32 s14, s0, 0x55555556
	s_lshr_b32 s15, s14, 31
	s_add_i32 s14, s14, s15
	s_mul_i32 s14, s14, 3
	s_sub_i32 s0, s0, s14
	s_lshl_b32 s30, s26, 6
	s_lshl_b32 s0, s0, 14
	s_add_i32 s14, s30, s24
	s_add_i32 s27, s27, 0x10000
	s_add_i32 s0, s0, 0
	s_lshl_b32 s26, s26, 8
	s_or_b32 s15, s14, 31
	s_add_i32 s31, s25, 0xffffff80
	s_cmp_lt_i32 s15, s31
	s_cselect_b64 s[38:39], -1, 0
	s_addk_i32 s25, 0x9f
	s_cmp_gt_i32 s14, s25
	s_cselect_b64 s[40:41], -1, 0
	s_or_b64 s[38:39], s[38:39], s[40:41]
	v_add_u32_e32 v100, s0, v70
	v_add_u32_e32 v99, s0, v71
	v_add3_u32 v66, v72, v73, s0
	s_movk_i32 s0, 0x60
	s_and_b64 vcc, exec, s[38:39]
	v_add_u32_e32 v98, v66, v74
	v_xad_u32 v97, v74, 32, v66
	v_xad_u32 v0, v74, 64, v66
	v_xad_u32 v96, v74, s0, v66
	s_cbranch_vccnz .LBB0_359
	s_add_i32 s0, s27, s26
	v_lshl_add_u32 v66, v93, 4, s0
	ds_read_b128 v[102:105], v100
	ds_read_b128 v[106:109], v100 offset:2048
	ds_read_b128 v[110:113], v99
	ds_read_b128 v[118:121], v99 offset:2048
	ds_read_b128 v[122:125], v66
	ds_read_b128 v[126:129], v66 offset:64
	v_lshl_add_u32 v66, v94, 4, s0
	ds_read_b128 v[130:133], v66
	ds_read_b128 v[134:137], v66 offset:64
	ds_read_b64_tr_b16 v[78:79], v98 offset:8192
	ds_read_b64_tr_b16 v[80:81], v98 offset:10240
	ds_read_b64_tr_b16 v[74:75], v97 offset:8192
	ds_read_b64_tr_b16 v[76:77], v97 offset:10240
	ds_read_b64_tr_b16 v[70:71], v0 offset:8192
	ds_read_b64_tr_b16 v[72:73], v0 offset:10240
	ds_read_b64_tr_b16 v[66:67], v96 offset:8192
	ds_read_b64_tr_b16 v[68:69], v96 offset:10240
	s_setprio 1
	s_waitcnt lgkmcnt(11)
	v_mfma_f32_16x16x32_bf16 v[122:125], v[102:105], v[30:33], v[122:125]
	s_waitcnt lgkmcnt(10)
	v_mfma_f32_16x16x32_bf16 v[126:129], v[106:109], v[30:33], v[126:129]
	s_waitcnt lgkmcnt(9)
	v_mfma_f32_16x16x32_bf16 v[102:105], v[102:105], v[22:25], v[130:133]
	s_waitcnt lgkmcnt(8)
	v_mfma_f32_16x16x32_bf16 v[106:109], v[106:109], v[22:25], v[134:137]
	v_mfma_f32_16x16x32_bf16 v[102:105], v[110:113], v[18:21], v[102:105]
	v_mfma_f32_16x16x32_bf16 v[106:109], v[118:121], v[18:21], v[106:109]
	v_mfma_f32_16x16x32_bf16 v[122:125], v[110:113], v[26:29], v[122:125]
	s_nop 5
	s_setprio 0
	v_maximum3_f32 v111, v102, v103, v104
	v_maximum3_f32 v113, v105, v106, v107
	v_maximum3_f32 v115, v108, v109, v109
	v_mfma_f32_16x16x32_bf16 v[126:129], v[118:121], v[26:29], v[126:129]
	v_maximum3_f32 v111, v111, v113, v115
	v_maximum3_f32 v83, v122, v123, v124
	v_mov_b32_e32 v113, v111
	s_nop 1
	v_permlane16_swap_b32_e32 v111, v113
	v_maximum3_f32 v111, v111, v113, v113
	s_nop 0
	v_maximum3_f32 v84, v125, v126, v127
	v_maximum3_f32 v85, v128, v129, v129
	v_maximum3_f32 v83, v83, v84, v85
	v_mov_b32_e32 v84, v83
	s_nop 1
	v_permlane16_swap_b32_e32 v83, v84
	v_maximum3_f32 v83, v83, v84, v84
	v_mov_b32_e32 v113, v111
	v_mov_b32_e32 v84, v83
	s_nop 0
	v_permlane32_swap_b32_e32 v111, v113
	v_permlane32_swap_b32_e32 v83, v84
	v_maximum3_f32 v117, v95, v111, v113
	v_maximum3_f32 v101, v82, v83, v84
	v_sub_f32_e32 v102, v102, v117
	v_sub_f32_e32 v83, v122, v101
	v_exp_f32_e32 v111, v102
	v_sub_f32_e32 v102, v103, v117
	v_exp_f32_e32 v110, v83
	v_sub_f32_e32 v83, v123, v101
	v_exp_f32_e32 v113, v102
	v_sub_f32_e32 v102, v104, v117
	v_exp_f32_e32 v112, v83
	v_sub_f32_e32 v83, v124, v101
	v_exp_f32_e32 v115, v102
	v_sub_f32_e32 v102, v105, v117
	v_exp_f32_e32 v114, v83
	v_sub_f32_e32 v83, v125, v101
	v_exp_f32_e32 v119, v102
	v_sub_f32_e32 v102, v106, v117
	v_exp_f32_e32 v118, v83
	v_sub_f32_e32 v83, v126, v101
	v_exp_f32_e32 v121, v102
	v_sub_f32_e32 v102, v107, v117
	v_sub_f32_e32 v82, v82, v101
	v_exp_f32_e32 v120, v83
	v_sub_f32_e32 v83, v127, v101
	v_exp_f32_e32 v123, v102
	v_sub_f32_e32 v102, v108, v117
	v_exp_f32_e32 v122, v83
	v_sub_f32_e32 v83, v128, v101
	v_exp_f32_e32 v128, v82
	v_pk_add_f32 v[130:131], v[110:111], 0 op_sel_hi:[1,0]
	v_exp_f32_e32 v125, v102
	v_sub_f32_e32 v102, v109, v117
	v_exp_f32_e32 v127, v102
	v_pk_add_f32 v[102:103], v[112:113], v[130:131]
	v_exp_f32_e32 v124, v83
	v_sub_f32_e32 v83, v129, v101
	v_pk_add_f32 v[102:103], v[114:115], v[102:103]
	v_exp_f32_e32 v126, v83
	v_sub_f32_e32 v95, v95, v117
	v_pk_add_f32 v[102:103], v[118:119], v[102:103]
	v_pk_mul_f32 v[52:53], v[52:53], v[128:129] op_sel_hi:[1,0]
	v_pk_mul_f32 v[50:51], v[50:51], v[128:129] op_sel_hi:[1,0]
	v_pk_mul_f32 v[56:57], v[56:57], v[128:129] op_sel_hi:[1,0]
	v_pk_mul_f32 v[54:55], v[54:55], v[128:129] op_sel_hi:[1,0]
	v_pk_mul_f32 v[60:61], v[60:61], v[128:129] op_sel_hi:[1,0]
	v_pk_mul_f32 v[58:59], v[58:59], v[128:129] op_sel_hi:[1,0]
	v_pk_mul_f32 v[64:65], v[64:65], v[128:129] op_sel_hi:[1,0]
	v_pk_mul_f32 v[62:63], v[62:63], v[128:129] op_sel_hi:[1,0]
	v_exp_f32_e32 v129, v95
	v_pk_add_f32 v[102:103], v[120:121], v[102:103]
	v_cvt_pk_bf16_f32 v82, v110, v112
	v_pk_add_f32 v[102:103], v[122:123], v[102:103]
	v_cvt_pk_bf16_f32 v83, v114, v118
	v_pk_add_f32 v[102:103], v[124:125], v[102:103]
	v_cvt_pk_bf16_f32 v84, v120, v122
	v_pk_add_f32 v[102:103], v[126:127], v[102:103]
	v_cvt_pk_bf16_f32 v85, v124, v126
	v_pk_fma_f32 v[88:89], v[88:89], v[128:129], v[102:103]
	v_mov_b32_e32 v102, v129
	v_pk_mul_f32 v[36:37], v[36:37], v[102:103] op_sel_hi:[1,0]
	v_pk_mul_f32 v[34:35], v[34:35], v[102:103] op_sel_hi:[1,0]
	v_pk_mul_f32 v[40:41], v[40:41], v[102:103] op_sel_hi:[1,0]
	v_pk_mul_f32 v[38:39], v[38:39], v[102:103] op_sel_hi:[1,0]
	v_pk_mul_f32 v[44:45], v[44:45], v[102:103] op_sel_hi:[1,0]
	v_pk_mul_f32 v[42:43], v[42:43], v[102:103] op_sel_hi:[1,0]
	v_pk_mul_f32 v[48:49], v[48:49], v[102:103] op_sel_hi:[1,0]
	v_pk_mul_f32 v[46:47], v[46:47], v[102:103] op_sel_hi:[1,0]
	v_cvt_pk_bf16_f32 v102, v111, v113
	v_cvt_pk_bf16_f32 v103, v115, v119
	v_cvt_pk_bf16_f32 v104, v121, v123
	v_cvt_pk_bf16_f32 v105, v125, v127
	s_setprio 1
	s_waitcnt lgkmcnt(6)
	v_mfma_f32_16x16x32_bf16 v[50:53], v[78:81], v[82:85], v[50:53]
	s_waitcnt lgkmcnt(4)
	v_mfma_f32_16x16x32_bf16 v[54:57], v[74:77], v[82:85], v[54:57]
	s_waitcnt lgkmcnt(2)
	v_mfma_f32_16x16x32_bf16 v[58:61], v[70:73], v[82:85], v[58:61]
	s_waitcnt lgkmcnt(0)
	v_mfma_f32_16x16x32_bf16 v[62:65], v[66:69], v[82:85], v[62:65]
	v_mfma_f32_16x16x32_bf16 v[34:37], v[78:81], v[102:105], v[34:37]
	v_mfma_f32_16x16x32_bf16 v[38:41], v[74:77], v[102:105], v[38:41]
	v_mfma_f32_16x16x32_bf16 v[42:45], v[70:73], v[102:105], v[42:45]
	v_mfma_f32_16x16x32_bf16 v[46:49], v[66:69], v[102:105], v[46:49]
	s_setprio 0
	v_mov_b32_e32 v82, v101
	v_mov_b32_e32 v95, v117
; #define LAS __attribute__((address_space(3)))
; template <int MODE> ...
;     ...
;             if (MODE == 1) { const int ks = ktok0 + 64 * t + 32 * hf;
;                 if (ks + 31 < qtok0 - 128 || ks > qtok0 + 31 + 128) continue; }
;             bf16x8 kf[2][2][2];
; #pragma unroll
;             for (int jj = 0; jj < 2; ++jj)
; #pragma unroll
;                 for (int kt = 0; kt < 2; ++kt)
; #pragma unroll
;                     for (int ks = 0; ks < 2; ++ks) kf[jj][kt][ks] = *(const LAS bf16x8*)(Sl + kad[jj][ks] + (32 * hf + 16 * kt) * 128);
;             f32x4 bb[2][2];
; #pragma unroll
;             for (int jj = 0; jj < 2; ++jj) { const LAS f32x4* bl = bcp + ((MODE == 0) ? (dr0 + t - act0) * 8 : 16 * t + 8 * hf) + bofs[jj];
; #pragma unroll
;                 for (int kt = 0; kt < 2; ++kt) bb[jj][kt] = bl[4 * kt]; }
;             s16x4 vlo[2][4], vhi[2][4];
; #pragma unroll
;             for (int jj = 0; jj < 2; ++jj)
; #pragma unroll
;                 for (int dt = 0; dt < 4; ++dt) { const LAS unsigned char* vp = Sl + vad[jj] + (32 * hf) * 128 + ((dt ^ sv) << 5);
;                     vlo[jj][dt] = __builtin_bit_cast(s16x4, __builtin_amdgcn_ds_read_tr16_b64_v4i16((LAS s16x4*)(vp)));
;                     vhi[jj][dt] = __builtin_bit_cast(s16x4, __builtin_amdgcn_ds_read_tr16_b64_v4i16((LAS s16x4*)(vp + 2048))); }
;             __builtin_amdgcn_sched_barrier(0);
;             f32x4 s[2][2];
; #pragma unroll
;             for (int jj = 0; jj < 2; ++jj)
; #pragma unroll
;                 for (int kt = 0; kt < 2; ++kt) { f32x4 a = (MODE == 0) ? bb[jj][kt] + mneg[jj][kt] : bb[jj][kt];
;                     a = __builtin_amdgcn_mfma_f32_16x16x32_bf16(kf[jj][kt][0], qf[jj][0], a, 0, 0, 0);
;                     s[jj][kt] = __builtin_amdgcn_mfma_f32_16x16x32_bf16(kf[jj][kt][1], qf[jj][1], a, 0, 0, 0); }
;             u32x4 pw[2];
; #pragma unroll
;             for (int jj = 0; jj < 2; ++jj) {
;                 const float tm = vmax3(vmax3(s[jj][0][0], s[jj][0][1], s[jj][0][2]), vmax3(s[jj][0][3], s[jj][1][0], s[jj][1][1]), vmax3(s[jj][1][2], s[jj][1][3], s[jj][1][3]));
;                 const float mn = quad_max3(mrun[jj], tm);
;                 const float alpha = __builtin_amdgcn_exp2f(mrun[jj] - mn);
;                 mrun[jj] = mn;
;                 float rsum = 0.f;
; #pragma unroll
;                 for (int kt = 0; kt < 2; ++kt)
; #pragma unroll
.LBB0_359:
	s_or_b32 s0, s30, 32
	s_add_i32 s0, s0, s24
	s_or_b32 s14, s0, 31
	s_cmp_lt_i32 s14, s31
	s_cselect_b64 s[30:31], -1, 0
	s_cmp_gt_i32 s0, s25
	s_cselect_b64 s[24:25], -1, 0
	s_or_b64 s[24:25], s[30:31], s[24:25]
	s_and_b64 vcc, exec, s[24:25]
	s_cbranch_vccnz .LBB0_361
	s_add_i32 s27, s27, s26
	v_lshl_add_u32 v83, v93, 4, s27
	ds_read_b128 v[66:69], v100 offset:4096
	ds_read_b128 v[70:73], v100 offset:6144
	ds_read_b128 v[74:77], v99 offset:4096
	ds_read_b128 v[78:81], v99 offset:6144
	ds_read_b128 v[100:103], v83 offset:128
	ds_read_b128 v[104:107], v83 offset:192
	v_lshl_add_u32 v83, v94, 4, s27
	ds_read_b128 v[108:111], v83 offset:128
	ds_read_b128 v[112:115], v83 offset:192
	ds_read_b64_tr_b16 v[118:119], v98 offset:12288
	ds_read_b64_tr_b16 v[120:121], v98 offset:14336
	ds_read_b64_tr_b16 v[122:123], v97 offset:12288
	ds_read_b64_tr_b16 v[124:125], v97 offset:14336
	ds_read_b64_tr_b16 v[126:127], v0 offset:12288
	ds_read_b64_tr_b16 v[128:129], v0 offset:14336
	ds_read_b64_tr_b16 v[130:131], v96 offset:12288
	ds_read_b64_tr_b16 v[132:133], v96 offset:14336
	s_setprio 1
	s_waitcnt lgkmcnt(11)
	v_mfma_f32_16x16x32_bf16 v[96:99], v[66:69], v[30:33], v[100:103]
	s_waitcnt lgkmcnt(10)
	v_mfma_f32_16x16x32_bf16 v[30:33], v[70:73], v[30:33], v[104:107]
	v_mfma_f32_16x16x32_bf16 v[96:99], v[74:77], v[26:29], v[96:99]
	v_mfma_f32_16x16x32_bf16 v[26:29], v[78:81], v[26:29], v[30:33]
	s_nop 6
	s_setprio 0
	v_maximum3_f32 v0, v96, v97, v98
	v_maximum3_f32 v30, v99, v26, v27
	v_maximum3_f32 v31, v28, v29, v29
	v_maximum3_f32 v0, v0, v30, v31
	v_mov_b32_e32 v30, v0
	s_nop 1
	v_permlane16_swap_b32_e32 v0, v30
	v_maximum3_f32 v0, v0, v30, v30
	v_mov_b32_e32 v30, v0
	s_nop 1
	v_permlane32_swap_b32_e32 v0, v30
	v_maximum3_f32 v0, v82, v0, v30
	s_waitcnt lgkmcnt(9)
	v_mfma_f32_16x16x32_bf16 v[30:33], v[66:69], v[22:25], v[108:111]
	v_sub_f32_e32 v83, v82, v0
	v_sub_f32_e32 v66, v97, v0
	v_exp_f32_e32 v84, v66
	s_waitcnt lgkmcnt(8)
	v_mfma_f32_16x16x32_bf16 v[22:25], v[70:73], v[22:25], v[112:115]
	v_sub_f32_e32 v66, v98, v0
	v_sub_f32_e32 v82, v96, v0
	v_sub_f32_e32 v26, v26, v0
	v_mfma_f32_16x16x32_bf16 v[30:33], v[74:77], v[18:21], v[30:33]
	v_exp_f32_e32 v74, v66
	v_sub_f32_e32 v66, v99, v0
	v_exp_f32_e32 v82, v82
	v_mfma_f32_16x16x32_bf16 v[18:21], v[78:81], v[18:21], v[22:25]
	v_exp_f32_e32 v78, v83
	v_exp_f32_e32 v70, v66
	v_exp_f32_e32 v72, v26
	v_sub_f32_e32 v22, v27, v0
	v_exp_f32_e32 v76, v22
	v_sub_f32_e32 v22, v28, v0
	v_sub_f32_e32 v0, v29, v0
	v_exp_f32_e32 v80, v22
	v_exp_f32_e32 v94, v0
	v_pk_mul_f32 v[22:23], v[50:51], v[78:79] op_sel_hi:[1,0]
	v_maximum3_f32 v0, v30, v31, v32
	v_maximum3_f32 v50, v33, v18, v19
	v_maximum3_f32 v51, v20, v21, v21
	v_maximum3_f32 v0, v0, v50, v51
	v_mov_b32_e32 v50, v0
	s_nop 1
	v_permlane16_swap_b32_e32 v0, v50
	v_maximum3_f32 v0, v0, v50, v50
	v_mov_b32_e32 v50, v0
	s_nop 1
	v_permlane32_swap_b32_e32 v0, v50
	v_maximum3_f32 v0, v95, v0, v50
	v_sub_f32_e32 v30, v30, v0
	v_exp_f32_e32 v83, v30
	v_sub_f32_e32 v30, v31, v0
	v_exp_f32_e32 v85, v30
	v_sub_f32_e32 v30, v32, v0
	v_sub_f32_e32 v18, v18, v0
	v_exp_f32_e32 v75, v30
	v_sub_f32_e32 v30, v33, v0
	v_exp_f32_e32 v73, v18
	v_sub_f32_e32 v18, v19, v0
	v_sub_f32_e32 v50, v95, v0
	v_exp_f32_e32 v71, v30
	v_exp_f32_e32 v77, v18
	v_sub_f32_e32 v18, v20, v0
	v_pk_mul_f32 v[24:25], v[52:53], v[78:79] op_sel_hi:[1,0]
	v_pk_mul_f32 v[28:29], v[56:57], v[78:79] op_sel_hi:[1,0]
	v_pk_mul_f32 v[26:27], v[54:55], v[78:79] op_sel_hi:[1,0]
	v_pk_mul_f32 v[60:61], v[60:61], v[78:79] op_sel_hi:[1,0]
	v_pk_mul_f32 v[58:59], v[58:59], v[78:79] op_sel_hi:[1,0]
	v_pk_mul_f32 v[64:65], v[64:65], v[78:79] op_sel_hi:[1,0]
	v_pk_mul_f32 v[62:63], v[62:63], v[78:79] op_sel_hi:[1,0]
	v_exp_f32_e32 v81, v18
	v_sub_f32_e32 v0, v21, v0
	v_exp_f32_e32 v79, v50
	v_pk_add_f32 v[18:19], v[82:83], 0 op_sel_hi:[1,0]
	v_exp_f32_e32 v95, v0
	v_pk_add_f32 v[18:19], v[84:85], v[18:19]
	v_cvt_pk_bf16_f32 v66, v82, v84
	v_pk_add_f32 v[18:19], v[74:75], v[18:19]
	v_cvt_pk_bf16_f32 v67, v74, v70
	v_pk_add_f32 v[18:19], v[70:71], v[18:19]
	v_cvt_pk_bf16_f32 v68, v72, v76
	v_cvt_pk_bf16_f32 v69, v80, v94
	v_pk_add_f32 v[18:19], v[72:73], v[18:19]
	v_mov_b32_e32 v0, v79
	s_setprio 1
	s_waitcnt lgkmcnt(6)
	v_mfma_f32_16x16x32_bf16 v[50:53], v[118:121], v[66:69], v[22:25]
	v_pk_mul_f32 v[20:21], v[36:37], v[0:1] op_sel_hi:[1,0]
	s_waitcnt lgkmcnt(4)
	v_mfma_f32_16x16x32_bf16 v[54:57], v[122:125], v[66:69], v[26:29]
	v_cvt_pk_bf16_f32 v22, v83, v85
	v_cvt_pk_bf16_f32 v23, v75, v71
	v_cvt_pk_bf16_f32 v24, v73, v77
	v_pk_add_f32 v[26:27], v[76:77], v[18:19]
	v_pk_mul_f32 v[18:19], v[34:35], v[0:1] op_sel_hi:[1,0]
	v_cvt_pk_bf16_f32 v25, v81, v95
	s_waitcnt lgkmcnt(2)
	v_mfma_f32_16x16x32_bf16 v[58:61], v[126:129], v[66:69], v[58:61]
	v_pk_add_f32 v[26:27], v[80:81], v[26:27]
	v_pk_add_f32 v[26:27], v[94:95], v[26:27]
	v_mfma_f32_16x16x32_bf16 v[34:37], v[118:121], v[22:25], v[18:21]
	v_fma_f32 v88, v88, v78, v26
	v_fma_f32 v89, v89, v79, v27
	s_nop 0
	v_pk_mul_f32 v[20:21], v[40:41], v[0:1] op_sel_hi:[1,0]
	v_pk_mul_f32 v[18:19], v[38:39], v[0:1] op_sel_hi:[1,0]
	s_waitcnt lgkmcnt(0)
	v_mfma_f32_16x16x32_bf16 v[62:65], v[130:133], v[66:69], v[62:65]
	v_mfma_f32_16x16x32_bf16 v[38:41], v[122:125], v[22:25], v[18:21]
	s_setprio 0
	s_nop 2
	v_pk_mul_f32 v[20:21], v[44:45], v[0:1] op_sel_hi:[1,0]
	v_pk_mul_f32 v[18:19], v[42:43], v[0:1] op_sel_hi:[1,0]
	s_nop 1
	v_mfma_f32_16x16x32_bf16 v[42:45], v[126:129], v[22:25], v[18:21]
	s_nop 2
	v_pk_mul_f32 v[20:21], v[48:49], v[0:1] op_sel_hi:[1,0]
	v_pk_mul_f32 v[18:19], v[46:47], v[0:1] op_sel_hi:[1,0]
	s_nop 1
	v_mfma_f32_16x16x32_bf16 v[46:49], v[130:133], v[22:25], v[18:21]
